# short-conv group rewritten by hand: 4-row-deep load pipeline, rotating tap registers
# baseline (speedup 1.0000x reference)
; __device__ __forceinline__ float bf_lo(unsigned w) { return __uint_as_float(w << 16); }
; __device__ __forceinline__ float bf_hi(unsigned w) { return __uint_as_float(w & 0xffff0000u); }
; __global__ void __launch_bounds__(512, 2) trunk_fwd(Args args) {
;     ...
;             for (int ch = gw; ch < M / 16; ch += NGW) {
;                 const int r0 = ch * 16, t0 = r0 & (SEQ - 1), c0 = lane * 8;
;                 float w0[8], w1[8], w2[8], u1[8], u2[8];
; #pragma unroll
;                 for (int i = 0; i < 8; ++i) { w0[i] = cw[c0 + i]; w1[i] = cw[512 + c0 + i]; w2[i] = cw[1024 + c0 + i]; u1[i] = 0.f; u2[i] = 0.f; }
;                 if (t0 != 0) {
;                     const u32x4 c1 = *(const u32x4*)(Z + (size_t)(r0 - 1) * INP + 1280 + c0), c2 = *(const u32x4*)(Z + (size_t)(r0 - 2) * INP + 1280 + c0);
; #pragma unroll
;                     for (int i = 0; i < 4; ++i) { u1[2 * i] = bf_lo(c1[i]); u1[2 * i + 1] = bf_hi(c1[i]); u2[2 * i] = bf_lo(c2[i]); u2[2 * i + 1] = bf_hi(c2[i]); }
;                 }
;                 u32x4 gb_n = *(const u32x4*)(Z + (size_t)r0 * INP + 768 + c0), gu_n = *(const u32x4*)(Z + (size_t)r0 * INP + 1280 + c0);
;                 f32x4 pv_n = *(const f32x4*)(pl + (size_t)r0 * PLE + lane * 4);
; #pragma nounroll
;                 for (int rr = 0; rr < 16; ++rr) {
;                     const int r = r0 + rr;
;                     const u32x4 gb = gb_n, gu = gu_n; const f32x4 pv4 = pv_n;
;                     if (rr < 15) { gb_n = *(const u32x4*)(Z + (size_t)(r + 1) * INP + 768 + c0); gu_n = *(const u32x4*)(Z + (size_t)(r + 1) * INP + 1280 + c0);
;                                    pv_n = *(const f32x4*)(pl + (size_t)(r + 1) * PLE + lane * 4); }
.LBB0_1054:
	s_lshl_b32 s42, s40, 4
	s_mov_b32 s43, 0
	s_mov_b32 s41, s42
	global_load_dwordx4 v[164:167], v[54:55], off
	global_load_dwordx4 v[168:171], v[54:55], off offset:16
	global_load_dwordx4 v[172:175], v[54:55], off offset:2048
	global_load_dwordx4 v[176:179], v[54:55], off offset:2064
	global_load_dwordx4 v[180:183], v[56:57], off
	global_load_dwordx4 v[184:187], v[56:57], off offset:16
	s_and_b32 s0, s42, 0xfff
	s_cmp_lg_u32 s0, 0
	s_cselect_b32 s1, 1, 0
	s_sub_u32 s0, s42, s1
	v_mad_i64_i32 v[160:161], vcc, s0, v221, v[58:59]
	s_sub_u32 s0, s0, s1
	global_load_dwordx4 v[30:33], v[160:161], off offset:2560
	v_mad_i64_i32 v[160:161], vcc, s0, v221, v[58:59]
	global_load_dwordx4 v[26:29], v[160:161], off offset:2560
	s_lshl_b64 s[0:1], s[42:43], 10
	v_lshl_add_u64 v[154:155], v[50:51], 0, s[0:1]
	s_lshl_b64 s[0:1], s[42:43], 9
	v_lshl_add_u64 v[158:159], v[52:53], 0, s[0:1]
	s_lshl_b64 s[0:1], s[42:43], 11
	s_add_u32 s0, s0, 0x19500400
	s_addc_u32 s1, s1, 0
	s_add_u32 s0, s0, s38
	s_addc_u32 s1, s1, s39
	v_lshl_add_u64 v[156:157], s[0:1], 0, v[0:1]
	s_waitcnt vmcnt(0)
	v_lshlrev_b32_e32 v204, 16, v30
	v_and_b32_e32 v205, 0xffff0000, v30
	v_lshlrev_b32_e32 v206, 16, v31
	v_and_b32_e32 v207, 0xffff0000, v31
	v_lshlrev_b32_e32 v208, 16, v32
	v_and_b32_e32 v209, 0xffff0000, v32
	v_lshlrev_b32_e32 v210, 16, v33
	v_and_b32_e32 v211, 0xffff0000, v33
	v_lshlrev_b32_e32 v196, 16, v26
	v_and_b32_e32 v197, 0xffff0000, v26
	v_lshlrev_b32_e32 v198, 16, v27
	v_and_b32_e32 v199, 0xffff0000, v27
	v_lshlrev_b32_e32 v200, 16, v28
	v_and_b32_e32 v201, 0xffff0000, v28
	v_lshlrev_b32_e32 v202, 16, v29
	v_and_b32_e32 v203, 0xffff0000, v29
	s_and_b32 s0, s42, 0xfff
	s_cmp_lg_u32 s0, 0
	s_cbranch_scc1 .Lcv_taps_ok
	v_mov_b32_e32 v204, 0
	v_mov_b32_e32 v205, 0
	v_mov_b32_e32 v206, 0
	v_mov_b32_e32 v207, 0
	v_mov_b32_e32 v208, 0
	v_mov_b32_e32 v209, 0
	v_mov_b32_e32 v210, 0
	v_mov_b32_e32 v211, 0
	v_mov_b32_e32 v196, 0
	v_mov_b32_e32 v197, 0
	v_mov_b32_e32 v198, 0
	v_mov_b32_e32 v199, 0
	v_mov_b32_e32 v200, 0
	v_mov_b32_e32 v201, 0
	v_mov_b32_e32 v202, 0
	v_mov_b32_e32 v203, 0
.Lcv_taps_ok:
	v_mad_i64_i32 v[152:153], vcc, s41, v221, v[58:59]
	s_add_u32 s41, s41, 1
	global_load_dwordx4 v[2:5], v[152:153], off offset:1536
	global_load_dwordx4 v[18:21], v[152:153], off offset:2560
	global_load_dwordx4 v[34:37], v[154:155], off
	v_mad_i64_i32 v[152:153], vcc, s41, v221, v[58:59]
	s_add_u32 s41, s41, 1
	global_load_dwordx4 v[6:9], v[152:153], off offset:1536
	global_load_dwordx4 v[22:25], v[152:153], off offset:2560
	global_load_dwordx4 v[38:41], v[154:155], off offset:1024
	v_mad_i64_i32 v[152:153], vcc, s41, v221, v[58:59]
	s_add_u32 s41, s41, 1
	global_load_dwordx4 v[10:13], v[152:153], off offset:1536
	global_load_dwordx4 v[26:29], v[152:153], off offset:2560
	global_load_dwordx4 v[42:45], v[154:155], off offset:2048
	v_mad_i64_i32 v[152:153], vcc, s41, v221, v[58:59]
	s_add_u32 s41, s41, 1
	global_load_dwordx4 v[14:17], v[152:153], off offset:1536
	global_load_dwordx4 v[30:33], v[152:153], off offset:2560
	global_load_dwordx4 v[46:49], v[154:155], off offset:3072
	v_lshl_add_u64 v[154:155], v[154:155], 0, s[20:21]
	s_waitcnt vmcnt(9)
	v_lshlrev_b32_e32 v188, 16, v18
	v_and_b32_e32 v189, 0xffff0000, v18
	v_lshlrev_b32_e32 v190, 16, v19
	v_and_b32_e32 v191, 0xffff0000, v19
	v_lshlrev_b32_e32 v192, 16, v20
	v_and_b32_e32 v193, 0xffff0000, v20
	v_lshlrev_b32_e32 v194, 16, v21
	v_and_b32_e32 v195, 0xffff0000, v21
	v_mul_f32_e32 v140, v164, v188
	v_mul_f32_e32 v141, v165, v189
	v_mul_f32_e32 v142, v166, v190
	v_mul_f32_e32 v143, v167, v191
	v_mul_f32_e32 v144, v168, v192
	v_mul_f32_e32 v145, v169, v193
	v_mul_f32_e32 v146, v170, v194
	v_mul_f32_e32 v147, v171, v195
	v_fmac_f32_e32 v140, v172, v204
	v_fmac_f32_e32 v141, v173, v205
	v_fmac_f32_e32 v142, v174, v206
	v_fmac_f32_e32 v143, v175, v207
	v_fmac_f32_e32 v144, v176, v208
	v_fmac_f32_e32 v145, v177, v209
	v_fmac_f32_e32 v146, v178, v210
	v_fmac_f32_e32 v147, v179, v211
	v_fmac_f32_e32 v140, v180, v196
	v_fmac_f32_e32 v141, v181, v197
	v_fmac_f32_e32 v142, v182, v198
	v_fmac_f32_e32 v143, v183, v199
	v_fmac_f32_e32 v144, v184, v200
	v_fmac_f32_e32 v145, v185, v201
	v_fmac_f32_e32 v146, v186, v202
	v_fmac_f32_e32 v147, v187, v203
	v_lshlrev_b32_e32 v150, 16, v2
	v_and_b32_e32 v151, 0xffff0000, v2
	v_mul_f32_e32 v140, v150, v140
	v_mul_f32_e32 v141, v151, v141
	v_lshlrev_b32_e32 v150, 16, v3
	v_and_b32_e32 v151, 0xffff0000, v3
	v_mul_f32_e32 v142, v150, v142
	v_mul_f32_e32 v143, v151, v143
	v_lshlrev_b32_e32 v150, 16, v4
	v_and_b32_e32 v151, 0xffff0000, v4
	v_mul_f32_e32 v144, v150, v144
	v_mul_f32_e32 v145, v151, v145
	v_lshlrev_b32_e32 v150, 16, v5
	v_and_b32_e32 v151, 0xffff0000, v5
	v_mul_f32_e32 v146, v150, v146
	v_mul_f32_e32 v147, v151, v147
	v_mul_f32_e32 v148, v140, v140
	v_fmac_f32_e32 v148, v141, v141
	v_fmac_f32_e32 v148, v142, v142
	v_fmac_f32_e32 v148, v143, v143
	v_fmac_f32_e32 v148, v144, v144
	v_fmac_f32_e32 v148, v145, v145
	v_fmac_f32_e32 v148, v146, v146
	v_fmac_f32_e32 v148, v147, v147
	v_cvt_pk_bf16_f32 v150, v34, v35
	v_cvt_pk_bf16_f32 v151, v36, v37
	global_store_dwordx2 v[158:159], v[150:151], off
	v_mad_i64_i32 v[152:153], vcc, s41, v221, v[58:59]
	s_add_u32 s41, s41, 1
	global_load_dwordx4 v[2:5], v[152:153], off offset:1536
	global_load_dwordx4 v[18:21], v[152:153], off offset:2560
	global_load_dwordx4 v[34:37], v[154:155], off
	ds_bpermute_b32 v150, v80, v148
	s_waitcnt lgkmcnt(0)
	v_add_f32_e32 v148, v148, v150
	ds_bpermute_b32 v150, v81, v148
	s_waitcnt lgkmcnt(0)
	v_add_f32_e32 v148, v148, v150
	ds_bpermute_b32 v150, v82, v148
	s_waitcnt lgkmcnt(0)
; __device__ __forceinline__ unsigned cvt_pk_bf16(float lo, float hi) { unsigned r; asm volatile("v_cvt_pk_bf16_f32 %0, %1, %2" : "=v"(r) : "v"(lo), "v"(hi)); return r; }
; __device__ __forceinline__ float bf_lo(unsigned w) { return __uint_as_float(w << 16); }
; __device__ __forceinline__ float bf_hi(unsigned w) { return __uint_as_float(w & 0xffff0000u); }
; __global__ void __launch_bounds__(512, 2) trunk_fwd(Args args) {
;     ...
;                     float cv[8], uu[8]; float ss = 0.f;
; #pragma unroll
;                     for (int i = 0; i < 4; ++i) {
;                         uu[2 * i] = bf_lo(gu[i]); uu[2 * i + 1] = bf_hi(gu[i]);
;                         cv[2 * i] = bf_lo(gb[i]) * (w0[2 * i] * uu[2 * i] + w1[2 * i] * u1[2 * i] + w2[2 * i] * u2[2 * i]);
;                         cv[2 * i + 1] = bf_hi(gb[i]) * (w0[2 * i + 1] * uu[2 * i + 1] + w1[2 * i + 1] * u1[2 * i + 1] + w2[2 * i + 1] * u2[2 * i + 1]);
;                     }
; #pragma unroll
;                     for (int i = 0; i < 8; ++i) { ss += cv[i] * cv[i]; u2[i] = u1[i]; u1[i] = uu[i]; }
;                     ss = wave_sum(ss);
;                     const float rc = rsqrtf(ss * (1.0f / 512.0f) + EPS);
;                     u32x4 oc;
; #pragma unroll
;                     for (int i = 0; i < 4; ++i) oc[i] = cvt_pk_bf16(cv[2 * i] * rc, cv[2 * i + 1] * rc);
;                     *(u32x4*)(MIX + (size_t)r * 1024 + 512 + c0) = oc;
;                     u32x2 pw; pw.x = cvt_pk_bf16(pv4[0], pv4[1]); pw.y = cvt_pk_bf16(pv4[2], pv4[3]);
;                     *(u32x2*)(PB + (size_t)r * PLE + lane * 4) = pw;
;                 }
	v_add_f32_e32 v148, v148, v150
	ds_bpermute_b32 v150, v83, v148
	s_waitcnt lgkmcnt(0)
	v_add_f32_e32 v148, v148, v150
	ds_bpermute_b32 v150, v84, v148
	s_waitcnt lgkmcnt(0)
	v_add_f32_e32 v148, v148, v150
	ds_bpermute_b32 v150, v85, v148
	s_waitcnt lgkmcnt(0)
	v_add_f32_e32 v148, v148, v150
	v_fmamk_f32 v148, v148, 0x3b000000, v162
	v_mul_f32_e32 v150, 0x4b800000, v148
	v_cmp_gt_f32_e32 vcc, s31, v148
	s_nop 1
	v_cndmask_b32_e32 v148, v148, v150, vcc
	v_rsq_f32_e32 v148, v148
	s_nop 0
	v_mul_f32_e32 v150, 0x45800000, v148
	v_cndmask_b32_e32 v149, v148, v150, vcc
	v_mul_f32_e32 v140, v149, v140
	v_mul_f32_e32 v141, v149, v141
	v_mul_f32_e32 v142, v149, v142
	v_mul_f32_e32 v143, v149, v143
	v_mul_f32_e32 v144, v149, v144
	v_mul_f32_e32 v145, v149, v145
	v_mul_f32_e32 v146, v149, v146
	v_mul_f32_e32 v147, v149, v147
	v_cvt_pk_bf16_f32 v140, v140, v141
	v_cvt_pk_bf16_f32 v141, v142, v143
	v_cvt_pk_bf16_f32 v142, v144, v145
	v_cvt_pk_bf16_f32 v143, v146, v147
	global_store_dwordx4 v[156:157], v[140:143], off
	s_waitcnt vmcnt(11)
	v_lshlrev_b32_e32 v196, 16, v22
	v_and_b32_e32 v197, 0xffff0000, v22
	v_lshlrev_b32_e32 v198, 16, v23
	v_and_b32_e32 v199, 0xffff0000, v23
	v_lshlrev_b32_e32 v200, 16, v24
	v_and_b32_e32 v201, 0xffff0000, v24
	v_lshlrev_b32_e32 v202, 16, v25
	v_and_b32_e32 v203, 0xffff0000, v25
	v_mul_f32_e32 v140, v164, v196
	v_mul_f32_e32 v141, v165, v197
	v_mul_f32_e32 v142, v166, v198
	v_mul_f32_e32 v143, v167, v199
	v_mul_f32_e32 v144, v168, v200
	v_mul_f32_e32 v145, v169, v201
	v_mul_f32_e32 v146, v170, v202
	v_mul_f32_e32 v147, v171, v203
	v_fmac_f32_e32 v140, v172, v188
	v_fmac_f32_e32 v141, v173, v189
	v_fmac_f32_e32 v142, v174, v190
	v_fmac_f32_e32 v143, v175, v191
	v_fmac_f32_e32 v144, v176, v192
	v_fmac_f32_e32 v145, v177, v193
	v_fmac_f32_e32 v146, v178, v194
	v_fmac_f32_e32 v147, v179, v195
	v_fmac_f32_e32 v140, v180, v204
	v_fmac_f32_e32 v141, v181, v205
	v_fmac_f32_e32 v142, v182, v206
	v_fmac_f32_e32 v143, v183, v207
	v_fmac_f32_e32 v144, v184, v208
	v_fmac_f32_e32 v145, v185, v209
	v_fmac_f32_e32 v146, v186, v210
	v_fmac_f32_e32 v147, v187, v211
	v_lshlrev_b32_e32 v150, 16, v6
	v_and_b32_e32 v151, 0xffff0000, v6
	v_mul_f32_e32 v140, v150, v140
	v_mul_f32_e32 v141, v151, v141
	v_lshlrev_b32_e32 v150, 16, v7
	v_and_b32_e32 v151, 0xffff0000, v7
	v_mul_f32_e32 v142, v150, v142
	v_mul_f32_e32 v143, v151, v143
	v_lshlrev_b32_e32 v150, 16, v8
	v_and_b32_e32 v151, 0xffff0000, v8
	v_mul_f32_e32 v144, v150, v144
	v_mul_f32_e32 v145, v151, v145
	v_lshlrev_b32_e32 v150, 16, v9
	v_and_b32_e32 v151, 0xffff0000, v9
	v_mul_f32_e32 v146, v150, v146
	v_mul_f32_e32 v147, v151, v147
	v_mul_f32_e32 v148, v140, v140
	v_fmac_f32_e32 v148, v141, v141
	v_fmac_f32_e32 v148, v142, v142
	v_fmac_f32_e32 v148, v143, v143
	v_fmac_f32_e32 v148, v144, v144
	v_fmac_f32_e32 v148, v145, v145
	v_fmac_f32_e32 v148, v146, v146
	v_fmac_f32_e32 v148, v147, v147
	v_cvt_pk_bf16_f32 v150, v38, v39
	v_cvt_pk_bf16_f32 v151, v40, v41
	global_store_dwordx2 v[158:159], v[150:151], off offset:512
	v_mad_i64_i32 v[152:153], vcc, s41, v221, v[58:59]
	s_add_u32 s41, s41, 1
	global_load_dwordx4 v[6:9], v[152:153], off offset:1536
	global_load_dwordx4 v[22:25], v[152:153], off offset:2560
	global_load_dwordx4 v[38:41], v[154:155], off offset:1024
	ds_bpermute_b32 v150, v80, v148
	s_waitcnt lgkmcnt(0)
	v_add_f32_e32 v148, v148, v150
	ds_bpermute_b32 v150, v81, v148
	s_waitcnt lgkmcnt(0)
	v_add_f32_e32 v148, v148, v150
	ds_bpermute_b32 v150, v82, v148
	s_waitcnt lgkmcnt(0)
	v_add_f32_e32 v148, v148, v150
	ds_bpermute_b32 v150, v83, v148
	s_waitcnt lgkmcnt(0)
	v_add_f32_e32 v148, v148, v150
	ds_bpermute_b32 v150, v84, v148
	s_waitcnt lgkmcnt(0)
	v_add_f32_e32 v148, v148, v150
	ds_bpermute_b32 v150, v85, v148
	s_waitcnt lgkmcnt(0)
	v_add_f32_e32 v148, v148, v150
	v_fmamk_f32 v148, v148, 0x3b000000, v162
	v_mul_f32_e32 v150, 0x4b800000, v148
	v_cmp_gt_f32_e32 vcc, s31, v148
	s_nop 1
	v_cndmask_b32_e32 v148, v148, v150, vcc
	v_rsq_f32_e32 v148, v148
	s_nop 0
	v_mul_f32_e32 v150, 0x45800000, v148
	v_cndmask_b32_e32 v149, v148, v150, vcc
	v_mul_f32_e32 v140, v149, v140
	v_mul_f32_e32 v141, v149, v141
	v_mul_f32_e32 v142, v149, v142
	v_mul_f32_e32 v143, v149, v143
	v_mul_f32_e32 v144, v149, v144
	v_mul_f32_e32 v145, v149, v145
	v_mul_f32_e32 v146, v149, v146
	v_mul_f32_e32 v147, v149, v147
	v_cvt_pk_bf16_f32 v140, v140, v141
	v_cvt_pk_bf16_f32 v141, v142, v143
	v_cvt_pk_bf16_f32 v142, v144, v145
	v_cvt_pk_bf16_f32 v143, v146, v147
	global_store_dwordx4 v[156:157], v[140:143], off offset:2048
	v_lshl_add_u64 v[156:157], v[156:157], 0, s[20:21]
	s_waitcnt vmcnt(13)
; __device__ __forceinline__ unsigned cvt_pk_bf16(float lo, float hi) { unsigned r; asm volatile("v_cvt_pk_bf16_f32 %0, %1, %2" : "=v"(r) : "v"(lo), "v"(hi)); return r; }
; __device__ __forceinline__ float bf_lo(unsigned w) { return __uint_as_float(w << 16); }
; __device__ __forceinline__ float bf_hi(unsigned w) { return __uint_as_float(w & 0xffff0000u); }
; __global__ void __launch_bounds__(512, 2) trunk_fwd(Args args) {
;     ...
;                     float cv[8], uu[8]; float ss = 0.f;
; #pragma unroll
;                     for (int i = 0; i < 4; ++i) {
;                         uu[2 * i] = bf_lo(gu[i]); uu[2 * i + 1] = bf_hi(gu[i]);
;                         cv[2 * i] = bf_lo(gb[i]) * (w0[2 * i] * uu[2 * i] + w1[2 * i] * u1[2 * i] + w2[2 * i] * u2[2 * i]);
;                         cv[2 * i + 1] = bf_hi(gb[i]) * (w0[2 * i + 1] * uu[2 * i + 1] + w1[2 * i + 1] * u1[2 * i + 1] + w2[2 * i + 1] * u2[2 * i + 1]);
;                     }
; #pragma unroll
;                     for (int i = 0; i < 8; ++i) { ss += cv[i] * cv[i]; u2[i] = u1[i]; u1[i] = uu[i]; }
;                     ss = wave_sum(ss);
;                     const float rc = rsqrtf(ss * (1.0f / 512.0f) + EPS);
;                     u32x4 oc;
; #pragma unroll
;                     for (int i = 0; i < 4; ++i) oc[i] = cvt_pk_bf16(cv[2 * i] * rc, cv[2 * i + 1] * rc);
;                     *(u32x4*)(MIX + (size_t)r * 1024 + 512 + c0) = oc;
;                     u32x2 pw; pw.x = cvt_pk_bf16(pv4[0], pv4[1]); pw.y = cvt_pk_bf16(pv4[2], pv4[3]);
;                     *(u32x2*)(PB + (size_t)r * PLE + lane * 4) = pw;
;                 }
	v_lshlrev_b32_e32 v204, 16, v26
	v_and_b32_e32 v205, 0xffff0000, v26
	v_lshlrev_b32_e32 v206, 16, v27
	v_and_b32_e32 v207, 0xffff0000, v27
	v_lshlrev_b32_e32 v208, 16, v28
	v_and_b32_e32 v209, 0xffff0000, v28
	v_lshlrev_b32_e32 v210, 16, v29
	v_and_b32_e32 v211, 0xffff0000, v29
	v_mul_f32_e32 v140, v164, v204
	v_mul_f32_e32 v141, v165, v205
	v_mul_f32_e32 v142, v166, v206
	v_mul_f32_e32 v143, v167, v207
	v_mul_f32_e32 v144, v168, v208
	v_mul_f32_e32 v145, v169, v209
	v_mul_f32_e32 v146, v170, v210
	v_mul_f32_e32 v147, v171, v211
	v_fmac_f32_e32 v140, v172, v196
	v_fmac_f32_e32 v141, v173, v197
	v_fmac_f32_e32 v142, v174, v198
	v_fmac_f32_e32 v143, v175, v199
	v_fmac_f32_e32 v144, v176, v200
	v_fmac_f32_e32 v145, v177, v201
	v_fmac_f32_e32 v146, v178, v202
	v_fmac_f32_e32 v147, v179, v203
	v_fmac_f32_e32 v140, v180, v188
	v_fmac_f32_e32 v141, v181, v189
	v_fmac_f32_e32 v142, v182, v190
	v_fmac_f32_e32 v143, v183, v191
	v_fmac_f32_e32 v144, v184, v192
	v_fmac_f32_e32 v145, v185, v193
	v_fmac_f32_e32 v146, v186, v194
	v_fmac_f32_e32 v147, v187, v195
	v_lshlrev_b32_e32 v150, 16, v10
	v_and_b32_e32 v151, 0xffff0000, v10
	v_mul_f32_e32 v140, v150, v140
	v_mul_f32_e32 v141, v151, v141
	v_lshlrev_b32_e32 v150, 16, v11
	v_and_b32_e32 v151, 0xffff0000, v11
	v_mul_f32_e32 v142, v150, v142
	v_mul_f32_e32 v143, v151, v143
	v_lshlrev_b32_e32 v150, 16, v12
	v_and_b32_e32 v151, 0xffff0000, v12
	v_mul_f32_e32 v144, v150, v144
	v_mul_f32_e32 v145, v151, v145
	v_lshlrev_b32_e32 v150, 16, v13
	v_and_b32_e32 v151, 0xffff0000, v13
	v_mul_f32_e32 v146, v150, v146
	v_mul_f32_e32 v147, v151, v147
	v_mul_f32_e32 v148, v140, v140
	v_fmac_f32_e32 v148, v141, v141
	v_fmac_f32_e32 v148, v142, v142
	v_fmac_f32_e32 v148, v143, v143
	v_fmac_f32_e32 v148, v144, v144
	v_fmac_f32_e32 v148, v145, v145
	v_fmac_f32_e32 v148, v146, v146
	v_fmac_f32_e32 v148, v147, v147
	v_cvt_pk_bf16_f32 v150, v42, v43
	v_cvt_pk_bf16_f32 v151, v44, v45
	global_store_dwordx2 v[158:159], v[150:151], off offset:1024
	v_mad_i64_i32 v[152:153], vcc, s41, v221, v[58:59]
	s_add_u32 s41, s41, 1
	global_load_dwordx4 v[10:13], v[152:153], off offset:1536
	global_load_dwordx4 v[26:29], v[152:153], off offset:2560
	global_load_dwordx4 v[42:45], v[154:155], off offset:2048
	ds_bpermute_b32 v150, v80, v148
	s_waitcnt lgkmcnt(0)
	v_add_f32_e32 v148, v148, v150
	ds_bpermute_b32 v150, v81, v148
	s_waitcnt lgkmcnt(0)
	v_add_f32_e32 v148, v148, v150
	ds_bpermute_b32 v150, v82, v148
	s_waitcnt lgkmcnt(0)
	v_add_f32_e32 v148, v148, v150
	ds_bpermute_b32 v150, v83, v148
	s_waitcnt lgkmcnt(0)
	v_add_f32_e32 v148, v148, v150
	ds_bpermute_b32 v150, v84, v148
	s_waitcnt lgkmcnt(0)
	v_add_f32_e32 v148, v148, v150
	ds_bpermute_b32 v150, v85, v148
	s_waitcnt lgkmcnt(0)
	v_add_f32_e32 v148, v148, v150
	v_fmamk_f32 v148, v148, 0x3b000000, v162
	v_mul_f32_e32 v150, 0x4b800000, v148
	v_cmp_gt_f32_e32 vcc, s31, v148
	s_nop 1
	v_cndmask_b32_e32 v148, v148, v150, vcc
	v_rsq_f32_e32 v148, v148
	s_nop 0
	v_mul_f32_e32 v150, 0x45800000, v148
	v_cndmask_b32_e32 v149, v148, v150, vcc
	v_mul_f32_e32 v140, v149, v140
	v_mul_f32_e32 v141, v149, v141
	v_mul_f32_e32 v142, v149, v142
	v_mul_f32_e32 v143, v149, v143
	v_mul_f32_e32 v144, v149, v144
	v_mul_f32_e32 v145, v149, v145
	v_mul_f32_e32 v146, v149, v146
	v_mul_f32_e32 v147, v149, v147
	v_cvt_pk_bf16_f32 v140, v140, v141
	v_cvt_pk_bf16_f32 v141, v142, v143
	v_cvt_pk_bf16_f32 v142, v144, v145
	v_cvt_pk_bf16_f32 v143, v146, v147
	global_store_dwordx4 v[156:157], v[140:143], off
	s_waitcnt vmcnt(15)
	v_lshlrev_b32_e32 v188, 16, v30
	v_and_b32_e32 v189, 0xffff0000, v30
	v_lshlrev_b32_e32 v190, 16, v31
	v_and_b32_e32 v191, 0xffff0000, v31
	v_lshlrev_b32_e32 v192, 16, v32
	v_and_b32_e32 v193, 0xffff0000, v32
	v_lshlrev_b32_e32 v194, 16, v33
	v_and_b32_e32 v195, 0xffff0000, v33
	v_mul_f32_e32 v140, v164, v188
	v_mul_f32_e32 v141, v165, v189
	v_mul_f32_e32 v142, v166, v190
	v_mul_f32_e32 v143, v167, v191
	v_mul_f32_e32 v144, v168, v192
	v_mul_f32_e32 v145, v169, v193
	v_mul_f32_e32 v146, v170, v194
	v_mul_f32_e32 v147, v171, v195
	v_fmac_f32_e32 v140, v172, v204
	v_fmac_f32_e32 v141, v173, v205
	v_fmac_f32_e32 v142, v174, v206
	v_fmac_f32_e32 v143, v175, v207
	v_fmac_f32_e32 v144, v176, v208
	v_fmac_f32_e32 v145, v177, v209
	v_fmac_f32_e32 v146, v178, v210
	v_fmac_f32_e32 v147, v179, v211
	v_fmac_f32_e32 v140, v180, v196
	v_fmac_f32_e32 v141, v181, v197
	v_fmac_f32_e32 v142, v182, v198
	v_fmac_f32_e32 v143, v183, v199
	v_fmac_f32_e32 v144, v184, v200
	v_fmac_f32_e32 v145, v185, v201
	v_fmac_f32_e32 v146, v186, v202
	v_fmac_f32_e32 v147, v187, v203
	v_lshlrev_b32_e32 v150, 16, v14
	v_and_b32_e32 v151, 0xffff0000, v14
	v_mul_f32_e32 v140, v150, v140
	v_mul_f32_e32 v141, v151, v141
	v_lshlrev_b32_e32 v150, 16, v15
	v_and_b32_e32 v151, 0xffff0000, v15
	v_mul_f32_e32 v142, v150, v142
	v_mul_f32_e32 v143, v151, v143
	v_lshlrev_b32_e32 v150, 16, v16
	v_and_b32_e32 v151, 0xffff0000, v16
	v_mul_f32_e32 v144, v150, v144
	v_mul_f32_e32 v145, v151, v145
	v_lshlrev_b32_e32 v150, 16, v17
	v_and_b32_e32 v151, 0xffff0000, v17
	v_mul_f32_e32 v146, v150, v146
	v_mul_f32_e32 v147, v151, v147
	v_mul_f32_e32 v148, v140, v140
	v_fmac_f32_e32 v148, v141, v141
	v_fmac_f32_e32 v148, v142, v142
	v_fmac_f32_e32 v148, v143, v143
	v_fmac_f32_e32 v148, v144, v144
	v_fmac_f32_e32 v148, v145, v145
	v_fmac_f32_e32 v148, v146, v146
	v_fmac_f32_e32 v148, v147, v147
	v_cvt_pk_bf16_f32 v150, v46, v47
	v_cvt_pk_bf16_f32 v151, v48, v49
	global_store_dwordx2 v[158:159], v[150:151], off offset:1536
	v_mad_i64_i32 v[152:153], vcc, s41, v221, v[58:59]
	s_add_u32 s41, s41, 1
	global_load_dwordx4 v[14:17], v[152:153], off offset:1536
	global_load_dwordx4 v[30:33], v[152:153], off offset:2560
	global_load_dwordx4 v[46:49], v[154:155], off offset:3072
	v_lshl_add_u64 v[154:155], v[154:155], 0, s[20:21]
	ds_bpermute_b32 v150, v80, v148
	s_waitcnt lgkmcnt(0)
; __device__ __forceinline__ unsigned cvt_pk_bf16(float lo, float hi) { unsigned r; asm volatile("v_cvt_pk_bf16_f32 %0, %1, %2" : "=v"(r) : "v"(lo), "v"(hi)); return r; }
; __device__ __forceinline__ float bf_lo(unsigned w) { return __uint_as_float(w << 16); }
; __device__ __forceinline__ float bf_hi(unsigned w) { return __uint_as_float(w & 0xffff0000u); }
; __global__ void __launch_bounds__(512, 2) trunk_fwd(Args args) {
;     ...
;                     float cv[8], uu[8]; float ss = 0.f;
; #pragma unroll
;                     for (int i = 0; i < 4; ++i) {
;                         uu[2 * i] = bf_lo(gu[i]); uu[2 * i + 1] = bf_hi(gu[i]);
;                         cv[2 * i] = bf_lo(gb[i]) * (w0[2 * i] * uu[2 * i] + w1[2 * i] * u1[2 * i] + w2[2 * i] * u2[2 * i]);
;                         cv[2 * i + 1] = bf_hi(gb[i]) * (w0[2 * i + 1] * uu[2 * i + 1] + w1[2 * i + 1] * u1[2 * i + 1] + w2[2 * i + 1] * u2[2 * i + 1]);
;                     }
; #pragma unroll
;                     for (int i = 0; i < 8; ++i) { ss += cv[i] * cv[i]; u2[i] = u1[i]; u1[i] = uu[i]; }
;                     ss = wave_sum(ss);
;                     const float rc = rsqrtf(ss * (1.0f / 512.0f) + EPS);
;                     u32x4 oc;
; #pragma unroll
;                     for (int i = 0; i < 4; ++i) oc[i] = cvt_pk_bf16(cv[2 * i] * rc, cv[2 * i + 1] * rc);
;                     *(u32x4*)(MIX + (size_t)r * 1024 + 512 + c0) = oc;
;                     u32x2 pw; pw.x = cvt_pk_bf16(pv4[0], pv4[1]); pw.y = cvt_pk_bf16(pv4[2], pv4[3]);
;                     *(u32x2*)(PB + (size_t)r * PLE + lane * 4) = pw;
;                 }
	v_add_f32_e32 v148, v148, v150
	ds_bpermute_b32 v150, v81, v148
	s_waitcnt lgkmcnt(0)
	v_add_f32_e32 v148, v148, v150
	ds_bpermute_b32 v150, v82, v148
	s_waitcnt lgkmcnt(0)
	v_add_f32_e32 v148, v148, v150
	ds_bpermute_b32 v150, v83, v148
	s_waitcnt lgkmcnt(0)
	v_add_f32_e32 v148, v148, v150
	ds_bpermute_b32 v150, v84, v148
	s_waitcnt lgkmcnt(0)
	v_add_f32_e32 v148, v148, v150
	ds_bpermute_b32 v150, v85, v148
	s_waitcnt lgkmcnt(0)
	v_add_f32_e32 v148, v148, v150
	v_fmamk_f32 v148, v148, 0x3b000000, v162
	v_mul_f32_e32 v150, 0x4b800000, v148
	v_cmp_gt_f32_e32 vcc, s31, v148
	s_nop 1
	v_cndmask_b32_e32 v148, v148, v150, vcc
	v_rsq_f32_e32 v148, v148
	s_nop 0
	v_mul_f32_e32 v150, 0x45800000, v148
	v_cndmask_b32_e32 v149, v148, v150, vcc
	v_mul_f32_e32 v140, v149, v140
	v_mul_f32_e32 v141, v149, v141
	v_mul_f32_e32 v142, v149, v142
	v_mul_f32_e32 v143, v149, v143
	v_mul_f32_e32 v144, v149, v144
	v_mul_f32_e32 v145, v149, v145
	v_mul_f32_e32 v146, v149, v146
	v_mul_f32_e32 v147, v149, v147
	v_cvt_pk_bf16_f32 v140, v140, v141
	v_cvt_pk_bf16_f32 v141, v142, v143
	v_cvt_pk_bf16_f32 v142, v144, v145
	v_cvt_pk_bf16_f32 v143, v146, v147
	global_store_dwordx4 v[156:157], v[140:143], off offset:2048
	v_lshl_add_u64 v[156:157], v[156:157], 0, s[20:21]
	s_waitcnt vmcnt(16)
	v_lshlrev_b32_e32 v196, 16, v18
	v_and_b32_e32 v197, 0xffff0000, v18
	v_lshlrev_b32_e32 v198, 16, v19
	v_and_b32_e32 v199, 0xffff0000, v19
	v_lshlrev_b32_e32 v200, 16, v20
	v_and_b32_e32 v201, 0xffff0000, v20
	v_lshlrev_b32_e32 v202, 16, v21
	v_and_b32_e32 v203, 0xffff0000, v21
	v_mul_f32_e32 v140, v164, v196
	v_mul_f32_e32 v141, v165, v197
	v_mul_f32_e32 v142, v166, v198
	v_mul_f32_e32 v143, v167, v199
	v_mul_f32_e32 v144, v168, v200
	v_mul_f32_e32 v145, v169, v201
	v_mul_f32_e32 v146, v170, v202
	v_mul_f32_e32 v147, v171, v203
	v_fmac_f32_e32 v140, v172, v188
	v_fmac_f32_e32 v141, v173, v189
	v_fmac_f32_e32 v142, v174, v190
	v_fmac_f32_e32 v143, v175, v191
	v_fmac_f32_e32 v144, v176, v192
	v_fmac_f32_e32 v145, v177, v193
	v_fmac_f32_e32 v146, v178, v194
	v_fmac_f32_e32 v147, v179, v195
	v_fmac_f32_e32 v140, v180, v204
	v_fmac_f32_e32 v141, v181, v205
	v_fmac_f32_e32 v142, v182, v206
	v_fmac_f32_e32 v143, v183, v207
	v_fmac_f32_e32 v144, v184, v208
	v_fmac_f32_e32 v145, v185, v209
	v_fmac_f32_e32 v146, v186, v210
	v_fmac_f32_e32 v147, v187, v211
	v_lshlrev_b32_e32 v150, 16, v2
	v_and_b32_e32 v151, 0xffff0000, v2
	v_mul_f32_e32 v140, v150, v140
	v_mul_f32_e32 v141, v151, v141
	v_lshlrev_b32_e32 v150, 16, v3
	v_and_b32_e32 v151, 0xffff0000, v3
	v_mul_f32_e32 v142, v150, v142
	v_mul_f32_e32 v143, v151, v143
	v_lshlrev_b32_e32 v150, 16, v4
	v_and_b32_e32 v151, 0xffff0000, v4
	v_mul_f32_e32 v144, v150, v144
	v_mul_f32_e32 v145, v151, v145
	v_lshlrev_b32_e32 v150, 16, v5
	v_and_b32_e32 v151, 0xffff0000, v5
	v_mul_f32_e32 v146, v150, v146
	v_mul_f32_e32 v147, v151, v147
	v_mul_f32_e32 v148, v140, v140
	v_fmac_f32_e32 v148, v141, v141
	v_fmac_f32_e32 v148, v142, v142
	v_fmac_f32_e32 v148, v143, v143
	v_fmac_f32_e32 v148, v144, v144
	v_fmac_f32_e32 v148, v145, v145
	v_fmac_f32_e32 v148, v146, v146
	v_fmac_f32_e32 v148, v147, v147
	v_cvt_pk_bf16_f32 v150, v34, v35
	v_cvt_pk_bf16_f32 v151, v36, v37
	global_store_dwordx2 v[158:159], v[150:151], off offset:2048
	v_mad_i64_i32 v[152:153], vcc, s41, v221, v[58:59]
	s_add_u32 s41, s41, 1
	global_load_dwordx4 v[2:5], v[152:153], off offset:1536
	global_load_dwordx4 v[18:21], v[152:153], off offset:2560
	global_load_dwordx4 v[34:37], v[154:155], off
	ds_bpermute_b32 v150, v80, v148
	s_waitcnt lgkmcnt(0)
	v_add_f32_e32 v148, v148, v150
	ds_bpermute_b32 v150, v81, v148
	s_waitcnt lgkmcnt(0)
	v_add_f32_e32 v148, v148, v150
	ds_bpermute_b32 v150, v82, v148
	s_waitcnt lgkmcnt(0)
	v_add_f32_e32 v148, v148, v150
	ds_bpermute_b32 v150, v83, v148
	s_waitcnt lgkmcnt(0)
	v_add_f32_e32 v148, v148, v150
	ds_bpermute_b32 v150, v84, v148
	s_waitcnt lgkmcnt(0)
	v_add_f32_e32 v148, v148, v150
	ds_bpermute_b32 v150, v85, v148
	s_waitcnt lgkmcnt(0)
	v_add_f32_e32 v148, v148, v150
	v_fmamk_f32 v148, v148, 0x3b000000, v162
	v_mul_f32_e32 v150, 0x4b800000, v148
	v_cmp_gt_f32_e32 vcc, s31, v148
	s_nop 1
	v_cndmask_b32_e32 v148, v148, v150, vcc
	v_rsq_f32_e32 v148, v148
	s_nop 0
	v_mul_f32_e32 v150, 0x45800000, v148
	v_cndmask_b32_e32 v149, v148, v150, vcc
	v_mul_f32_e32 v140, v149, v140
	v_mul_f32_e32 v141, v149, v141
	v_mul_f32_e32 v142, v149, v142
	v_mul_f32_e32 v143, v149, v143
	v_mul_f32_e32 v144, v149, v144
	v_mul_f32_e32 v145, v149, v145
	v_mul_f32_e32 v146, v149, v146
	v_mul_f32_e32 v147, v149, v147
	v_cvt_pk_bf16_f32 v140, v140, v141
	v_cvt_pk_bf16_f32 v141, v142, v143
	v_cvt_pk_bf16_f32 v142, v144, v145
	v_cvt_pk_bf16_f32 v143, v146, v147
	global_store_dwordx4 v[156:157], v[140:143], off
	s_waitcnt vmcnt(16)
; __device__ __forceinline__ unsigned cvt_pk_bf16(float lo, float hi) { unsigned r; asm volatile("v_cvt_pk_bf16_f32 %0, %1, %2" : "=v"(r) : "v"(lo), "v"(hi)); return r; }
; __device__ __forceinline__ float bf_lo(unsigned w) { return __uint_as_float(w << 16); }
; __device__ __forceinline__ float bf_hi(unsigned w) { return __uint_as_float(w & 0xffff0000u); }
; __global__ void __launch_bounds__(512, 2) trunk_fwd(Args args) {
;     ...
;                     float cv[8], uu[8]; float ss = 0.f;
; #pragma unroll
;                     for (int i = 0; i < 4; ++i) {
;                         uu[2 * i] = bf_lo(gu[i]); uu[2 * i + 1] = bf_hi(gu[i]);
;                         cv[2 * i] = bf_lo(gb[i]) * (w0[2 * i] * uu[2 * i] + w1[2 * i] * u1[2 * i] + w2[2 * i] * u2[2 * i]);
;                         cv[2 * i + 1] = bf_hi(gb[i]) * (w0[2 * i + 1] * uu[2 * i + 1] + w1[2 * i + 1] * u1[2 * i + 1] + w2[2 * i + 1] * u2[2 * i + 1]);
;                     }
; #pragma unroll
;                     for (int i = 0; i < 8; ++i) { ss += cv[i] * cv[i]; u2[i] = u1[i]; u1[i] = uu[i]; }
;                     ss = wave_sum(ss);
;                     const float rc = rsqrtf(ss * (1.0f / 512.0f) + EPS);
;                     u32x4 oc;
; #pragma unroll
;                     for (int i = 0; i < 4; ++i) oc[i] = cvt_pk_bf16(cv[2 * i] * rc, cv[2 * i + 1] * rc);
;                     *(u32x4*)(MIX + (size_t)r * 1024 + 512 + c0) = oc;
;                     u32x2 pw; pw.x = cvt_pk_bf16(pv4[0], pv4[1]); pw.y = cvt_pk_bf16(pv4[2], pv4[3]);
;                     *(u32x2*)(PB + (size_t)r * PLE + lane * 4) = pw;
;                 }
	v_lshlrev_b32_e32 v204, 16, v22
	v_and_b32_e32 v205, 0xffff0000, v22
	v_lshlrev_b32_e32 v206, 16, v23
	v_and_b32_e32 v207, 0xffff0000, v23
	v_lshlrev_b32_e32 v208, 16, v24
	v_and_b32_e32 v209, 0xffff0000, v24
	v_lshlrev_b32_e32 v210, 16, v25
	v_and_b32_e32 v211, 0xffff0000, v25
	v_mul_f32_e32 v140, v164, v204
	v_mul_f32_e32 v141, v165, v205
	v_mul_f32_e32 v142, v166, v206
	v_mul_f32_e32 v143, v167, v207
	v_mul_f32_e32 v144, v168, v208
	v_mul_f32_e32 v145, v169, v209
	v_mul_f32_e32 v146, v170, v210
	v_mul_f32_e32 v147, v171, v211
	v_fmac_f32_e32 v140, v172, v196
	v_fmac_f32_e32 v141, v173, v197
	v_fmac_f32_e32 v142, v174, v198
	v_fmac_f32_e32 v143, v175, v199
	v_fmac_f32_e32 v144, v176, v200
	v_fmac_f32_e32 v145, v177, v201
	v_fmac_f32_e32 v146, v178, v202
	v_fmac_f32_e32 v147, v179, v203
	v_fmac_f32_e32 v140, v180, v188
	v_fmac_f32_e32 v141, v181, v189
	v_fmac_f32_e32 v142, v182, v190
	v_fmac_f32_e32 v143, v183, v191
	v_fmac_f32_e32 v144, v184, v192
	v_fmac_f32_e32 v145, v185, v193
	v_fmac_f32_e32 v146, v186, v194
	v_fmac_f32_e32 v147, v187, v195
	v_lshlrev_b32_e32 v150, 16, v6
	v_and_b32_e32 v151, 0xffff0000, v6
	v_mul_f32_e32 v140, v150, v140
	v_mul_f32_e32 v141, v151, v141
	v_lshlrev_b32_e32 v150, 16, v7
	v_and_b32_e32 v151, 0xffff0000, v7
	v_mul_f32_e32 v142, v150, v142
	v_mul_f32_e32 v143, v151, v143
	v_lshlrev_b32_e32 v150, 16, v8
	v_and_b32_e32 v151, 0xffff0000, v8
	v_mul_f32_e32 v144, v150, v144
	v_mul_f32_e32 v145, v151, v145
	v_lshlrev_b32_e32 v150, 16, v9
	v_and_b32_e32 v151, 0xffff0000, v9
	v_mul_f32_e32 v146, v150, v146
	v_mul_f32_e32 v147, v151, v147
	v_mul_f32_e32 v148, v140, v140
	v_fmac_f32_e32 v148, v141, v141
	v_fmac_f32_e32 v148, v142, v142
	v_fmac_f32_e32 v148, v143, v143
	v_fmac_f32_e32 v148, v144, v144
	v_fmac_f32_e32 v148, v145, v145
	v_fmac_f32_e32 v148, v146, v146
	v_fmac_f32_e32 v148, v147, v147
	v_cvt_pk_bf16_f32 v150, v38, v39
	v_cvt_pk_bf16_f32 v151, v40, v41
	global_store_dwordx2 v[158:159], v[150:151], off offset:2560
	v_mad_i64_i32 v[152:153], vcc, s41, v221, v[58:59]
	s_add_u32 s41, s41, 1
	global_load_dwordx4 v[6:9], v[152:153], off offset:1536
	global_load_dwordx4 v[22:25], v[152:153], off offset:2560
	global_load_dwordx4 v[38:41], v[154:155], off offset:1024
	ds_bpermute_b32 v150, v80, v148
	s_waitcnt lgkmcnt(0)
	v_add_f32_e32 v148, v148, v150
	ds_bpermute_b32 v150, v81, v148
	s_waitcnt lgkmcnt(0)
	v_add_f32_e32 v148, v148, v150
	ds_bpermute_b32 v150, v82, v148
	s_waitcnt lgkmcnt(0)
	v_add_f32_e32 v148, v148, v150
	ds_bpermute_b32 v150, v83, v148
	s_waitcnt lgkmcnt(0)
	v_add_f32_e32 v148, v148, v150
	ds_bpermute_b32 v150, v84, v148
	s_waitcnt lgkmcnt(0)
	v_add_f32_e32 v148, v148, v150
	ds_bpermute_b32 v150, v85, v148
	s_waitcnt lgkmcnt(0)
	v_add_f32_e32 v148, v148, v150
	v_fmamk_f32 v148, v148, 0x3b000000, v162
	v_mul_f32_e32 v150, 0x4b800000, v148
	v_cmp_gt_f32_e32 vcc, s31, v148
	s_nop 1
	v_cndmask_b32_e32 v148, v148, v150, vcc
	v_rsq_f32_e32 v148, v148
	s_nop 0
	v_mul_f32_e32 v150, 0x45800000, v148
	v_cndmask_b32_e32 v149, v148, v150, vcc
	v_mul_f32_e32 v140, v149, v140
	v_mul_f32_e32 v141, v149, v141
	v_mul_f32_e32 v142, v149, v142
	v_mul_f32_e32 v143, v149, v143
	v_mul_f32_e32 v144, v149, v144
	v_mul_f32_e32 v145, v149, v145
	v_mul_f32_e32 v146, v149, v146
	v_mul_f32_e32 v147, v149, v147
	v_cvt_pk_bf16_f32 v140, v140, v141
	v_cvt_pk_bf16_f32 v141, v142, v143
	v_cvt_pk_bf16_f32 v142, v144, v145
	v_cvt_pk_bf16_f32 v143, v146, v147
	global_store_dwordx4 v[156:157], v[140:143], off offset:2048
	v_lshl_add_u64 v[156:157], v[156:157], 0, s[20:21]
	s_waitcnt vmcnt(16)
	v_lshlrev_b32_e32 v188, 16, v26
	v_and_b32_e32 v189, 0xffff0000, v26
	v_lshlrev_b32_e32 v190, 16, v27
	v_and_b32_e32 v191, 0xffff0000, v27
	v_lshlrev_b32_e32 v192, 16, v28
	v_and_b32_e32 v193, 0xffff0000, v28
	v_lshlrev_b32_e32 v194, 16, v29
	v_and_b32_e32 v195, 0xffff0000, v29
	v_mul_f32_e32 v140, v164, v188
	v_mul_f32_e32 v141, v165, v189
	v_mul_f32_e32 v142, v166, v190
	v_mul_f32_e32 v143, v167, v191
	v_mul_f32_e32 v144, v168, v192
	v_mul_f32_e32 v145, v169, v193
	v_mul_f32_e32 v146, v170, v194
	v_mul_f32_e32 v147, v171, v195
	v_fmac_f32_e32 v140, v172, v204
	v_fmac_f32_e32 v141, v173, v205
	v_fmac_f32_e32 v142, v174, v206
	v_fmac_f32_e32 v143, v175, v207
	v_fmac_f32_e32 v144, v176, v208
	v_fmac_f32_e32 v145, v177, v209
	v_fmac_f32_e32 v146, v178, v210
	v_fmac_f32_e32 v147, v179, v211
	v_fmac_f32_e32 v140, v180, v196
	v_fmac_f32_e32 v141, v181, v197
	v_fmac_f32_e32 v142, v182, v198
	v_fmac_f32_e32 v143, v183, v199
	v_fmac_f32_e32 v144, v184, v200
	v_fmac_f32_e32 v145, v185, v201
	v_fmac_f32_e32 v146, v186, v202
	v_fmac_f32_e32 v147, v187, v203
	v_lshlrev_b32_e32 v150, 16, v10
	v_and_b32_e32 v151, 0xffff0000, v10
	v_mul_f32_e32 v140, v150, v140
	v_mul_f32_e32 v141, v151, v141
	v_lshlrev_b32_e32 v150, 16, v11
	v_and_b32_e32 v151, 0xffff0000, v11
	v_mul_f32_e32 v142, v150, v142
	v_mul_f32_e32 v143, v151, v143
	v_lshlrev_b32_e32 v150, 16, v12
	v_and_b32_e32 v151, 0xffff0000, v12
	v_mul_f32_e32 v144, v150, v144
	v_mul_f32_e32 v145, v151, v145
	v_lshlrev_b32_e32 v150, 16, v13
	v_and_b32_e32 v151, 0xffff0000, v13
	v_mul_f32_e32 v146, v150, v146
	v_mul_f32_e32 v147, v151, v147
	v_mul_f32_e32 v148, v140, v140
	v_fmac_f32_e32 v148, v141, v141
	v_fmac_f32_e32 v148, v142, v142
	v_fmac_f32_e32 v148, v143, v143
	v_fmac_f32_e32 v148, v144, v144
	v_fmac_f32_e32 v148, v145, v145
	v_fmac_f32_e32 v148, v146, v146
	v_fmac_f32_e32 v148, v147, v147
	v_cvt_pk_bf16_f32 v150, v42, v43
	v_cvt_pk_bf16_f32 v151, v44, v45
	global_store_dwordx2 v[158:159], v[150:151], off offset:3072
	v_mad_i64_i32 v[152:153], vcc, s41, v221, v[58:59]
	s_add_u32 s41, s41, 1
	global_load_dwordx4 v[10:13], v[152:153], off offset:1536
	global_load_dwordx4 v[26:29], v[152:153], off offset:2560
	global_load_dwordx4 v[42:45], v[154:155], off offset:2048
	ds_bpermute_b32 v150, v80, v148
	s_waitcnt lgkmcnt(0)
; __device__ __forceinline__ unsigned cvt_pk_bf16(float lo, float hi) { unsigned r; asm volatile("v_cvt_pk_bf16_f32 %0, %1, %2" : "=v"(r) : "v"(lo), "v"(hi)); return r; }
; __device__ __forceinline__ float bf_lo(unsigned w) { return __uint_as_float(w << 16); }
; __device__ __forceinline__ float bf_hi(unsigned w) { return __uint_as_float(w & 0xffff0000u); }
; __global__ void __launch_bounds__(512, 2) trunk_fwd(Args args) {
;     ...
;                     float cv[8], uu[8]; float ss = 0.f;
; #pragma unroll
;                     for (int i = 0; i < 4; ++i) {
;                         uu[2 * i] = bf_lo(gu[i]); uu[2 * i + 1] = bf_hi(gu[i]);
;                         cv[2 * i] = bf_lo(gb[i]) * (w0[2 * i] * uu[2 * i] + w1[2 * i] * u1[2 * i] + w2[2 * i] * u2[2 * i]);
;                         cv[2 * i + 1] = bf_hi(gb[i]) * (w0[2 * i + 1] * uu[2 * i + 1] + w1[2 * i + 1] * u1[2 * i + 1] + w2[2 * i + 1] * u2[2 * i + 1]);
;                     }
; #pragma unroll
;                     for (int i = 0; i < 8; ++i) { ss += cv[i] * cv[i]; u2[i] = u1[i]; u1[i] = uu[i]; }
;                     ss = wave_sum(ss);
;                     const float rc = rsqrtf(ss * (1.0f / 512.0f) + EPS);
;                     u32x4 oc;
; #pragma unroll
;                     for (int i = 0; i < 4; ++i) oc[i] = cvt_pk_bf16(cv[2 * i] * rc, cv[2 * i + 1] * rc);
;                     *(u32x4*)(MIX + (size_t)r * 1024 + 512 + c0) = oc;
;                     u32x2 pw; pw.x = cvt_pk_bf16(pv4[0], pv4[1]); pw.y = cvt_pk_bf16(pv4[2], pv4[3]);
;                     *(u32x2*)(PB + (size_t)r * PLE + lane * 4) = pw;
;                 }
	v_add_f32_e32 v148, v148, v150
	ds_bpermute_b32 v150, v81, v148
	s_waitcnt lgkmcnt(0)
	v_add_f32_e32 v148, v148, v150
	ds_bpermute_b32 v150, v82, v148
	s_waitcnt lgkmcnt(0)
	v_add_f32_e32 v148, v148, v150
	ds_bpermute_b32 v150, v83, v148
	s_waitcnt lgkmcnt(0)
	v_add_f32_e32 v148, v148, v150
	ds_bpermute_b32 v150, v84, v148
	s_waitcnt lgkmcnt(0)
	v_add_f32_e32 v148, v148, v150
	ds_bpermute_b32 v150, v85, v148
	s_waitcnt lgkmcnt(0)
	v_add_f32_e32 v148, v148, v150
	v_fmamk_f32 v148, v148, 0x3b000000, v162
	v_mul_f32_e32 v150, 0x4b800000, v148
	v_cmp_gt_f32_e32 vcc, s31, v148
	s_nop 1
	v_cndmask_b32_e32 v148, v148, v150, vcc
	v_rsq_f32_e32 v148, v148
	s_nop 0
	v_mul_f32_e32 v150, 0x45800000, v148
	v_cndmask_b32_e32 v149, v148, v150, vcc
	v_mul_f32_e32 v140, v149, v140
	v_mul_f32_e32 v141, v149, v141
	v_mul_f32_e32 v142, v149, v142
	v_mul_f32_e32 v143, v149, v143
	v_mul_f32_e32 v144, v149, v144
	v_mul_f32_e32 v145, v149, v145
	v_mul_f32_e32 v146, v149, v146
	v_mul_f32_e32 v147, v149, v147
	v_cvt_pk_bf16_f32 v140, v140, v141
	v_cvt_pk_bf16_f32 v141, v142, v143
	v_cvt_pk_bf16_f32 v142, v144, v145
	v_cvt_pk_bf16_f32 v143, v146, v147
	global_store_dwordx4 v[156:157], v[140:143], off
	s_waitcnt vmcnt(16)
	v_lshlrev_b32_e32 v196, 16, v30
	v_and_b32_e32 v197, 0xffff0000, v30
	v_lshlrev_b32_e32 v198, 16, v31
	v_and_b32_e32 v199, 0xffff0000, v31
	v_lshlrev_b32_e32 v200, 16, v32
	v_and_b32_e32 v201, 0xffff0000, v32
	v_lshlrev_b32_e32 v202, 16, v33
	v_and_b32_e32 v203, 0xffff0000, v33
	v_mul_f32_e32 v140, v164, v196
	v_mul_f32_e32 v141, v165, v197
	v_mul_f32_e32 v142, v166, v198
	v_mul_f32_e32 v143, v167, v199
	v_mul_f32_e32 v144, v168, v200
	v_mul_f32_e32 v145, v169, v201
	v_mul_f32_e32 v146, v170, v202
	v_mul_f32_e32 v147, v171, v203
	v_fmac_f32_e32 v140, v172, v188
	v_fmac_f32_e32 v141, v173, v189
	v_fmac_f32_e32 v142, v174, v190
	v_fmac_f32_e32 v143, v175, v191
	v_fmac_f32_e32 v144, v176, v192
	v_fmac_f32_e32 v145, v177, v193
	v_fmac_f32_e32 v146, v178, v194
	v_fmac_f32_e32 v147, v179, v195
	v_fmac_f32_e32 v140, v180, v204
	v_fmac_f32_e32 v141, v181, v205
	v_fmac_f32_e32 v142, v182, v206
	v_fmac_f32_e32 v143, v183, v207
	v_fmac_f32_e32 v144, v184, v208
	v_fmac_f32_e32 v145, v185, v209
	v_fmac_f32_e32 v146, v186, v210
	v_fmac_f32_e32 v147, v187, v211
	v_lshlrev_b32_e32 v150, 16, v14
	v_and_b32_e32 v151, 0xffff0000, v14
	v_mul_f32_e32 v140, v150, v140
	v_mul_f32_e32 v141, v151, v141
	v_lshlrev_b32_e32 v150, 16, v15
	v_and_b32_e32 v151, 0xffff0000, v15
	v_mul_f32_e32 v142, v150, v142
	v_mul_f32_e32 v143, v151, v143
	v_lshlrev_b32_e32 v150, 16, v16
	v_and_b32_e32 v151, 0xffff0000, v16
	v_mul_f32_e32 v144, v150, v144
	v_mul_f32_e32 v145, v151, v145
	v_lshlrev_b32_e32 v150, 16, v17
	v_and_b32_e32 v151, 0xffff0000, v17
	v_mul_f32_e32 v146, v150, v146
	v_mul_f32_e32 v147, v151, v147
	v_mul_f32_e32 v148, v140, v140
	v_fmac_f32_e32 v148, v141, v141
	v_fmac_f32_e32 v148, v142, v142
	v_fmac_f32_e32 v148, v143, v143
	v_fmac_f32_e32 v148, v144, v144
	v_fmac_f32_e32 v148, v145, v145
	v_fmac_f32_e32 v148, v146, v146
	v_fmac_f32_e32 v148, v147, v147
	v_cvt_pk_bf16_f32 v150, v46, v47
	v_cvt_pk_bf16_f32 v151, v48, v49
	global_store_dwordx2 v[158:159], v[150:151], off offset:3584
	v_lshl_add_u64 v[158:159], v[158:159], 0, s[20:21]
	v_mad_i64_i32 v[152:153], vcc, s41, v221, v[58:59]
	s_add_u32 s41, s41, 1
	global_load_dwordx4 v[14:17], v[152:153], off offset:1536
	global_load_dwordx4 v[30:33], v[152:153], off offset:2560
	global_load_dwordx4 v[46:49], v[154:155], off offset:3072
	v_lshl_add_u64 v[154:155], v[154:155], 0, s[20:21]
	ds_bpermute_b32 v150, v80, v148
	s_waitcnt lgkmcnt(0)
	v_add_f32_e32 v148, v148, v150
	ds_bpermute_b32 v150, v81, v148
	s_waitcnt lgkmcnt(0)
	v_add_f32_e32 v148, v148, v150
	ds_bpermute_b32 v150, v82, v148
	s_waitcnt lgkmcnt(0)
	v_add_f32_e32 v148, v148, v150
	ds_bpermute_b32 v150, v83, v148
	s_waitcnt lgkmcnt(0)
	v_add_f32_e32 v148, v148, v150
	ds_bpermute_b32 v150, v84, v148
	s_waitcnt lgkmcnt(0)
	v_add_f32_e32 v148, v148, v150
	ds_bpermute_b32 v150, v85, v148
	s_waitcnt lgkmcnt(0)
	v_add_f32_e32 v148, v148, v150
	v_fmamk_f32 v148, v148, 0x3b000000, v162
	v_mul_f32_e32 v150, 0x4b800000, v148
	v_cmp_gt_f32_e32 vcc, s31, v148
	s_nop 1
	v_cndmask_b32_e32 v148, v148, v150, vcc
	v_rsq_f32_e32 v148, v148
	s_nop 0
	v_mul_f32_e32 v150, 0x45800000, v148
	v_cndmask_b32_e32 v149, v148, v150, vcc
	v_mul_f32_e32 v140, v149, v140
	v_mul_f32_e32 v141, v149, v141
	v_mul_f32_e32 v142, v149, v142
	v_mul_f32_e32 v143, v149, v143
	v_mul_f32_e32 v144, v149, v144
	v_mul_f32_e32 v145, v149, v145
	v_mul_f32_e32 v146, v149, v146
	v_mul_f32_e32 v147, v149, v147
	v_cvt_pk_bf16_f32 v140, v140, v141
	v_cvt_pk_bf16_f32 v141, v142, v143
	v_cvt_pk_bf16_f32 v142, v144, v145
	v_cvt_pk_bf16_f32 v143, v146, v147
	global_store_dwordx4 v[156:157], v[140:143], off offset:2048
	v_lshl_add_u64 v[156:157], v[156:157], 0, s[20:21]
	s_waitcnt vmcnt(16)
; __device__ __forceinline__ unsigned cvt_pk_bf16(float lo, float hi) { unsigned r; asm volatile("v_cvt_pk_bf16_f32 %0, %1, %2" : "=v"(r) : "v"(lo), "v"(hi)); return r; }
; __device__ __forceinline__ float bf_lo(unsigned w) { return __uint_as_float(w << 16); }
; __device__ __forceinline__ float bf_hi(unsigned w) { return __uint_as_float(w & 0xffff0000u); }
; __global__ void __launch_bounds__(512, 2) trunk_fwd(Args args) {
;     ...
;                     float cv[8], uu[8]; float ss = 0.f;
; #pragma unroll
;                     for (int i = 0; i < 4; ++i) {
;                         uu[2 * i] = bf_lo(gu[i]); uu[2 * i + 1] = bf_hi(gu[i]);
;                         cv[2 * i] = bf_lo(gb[i]) * (w0[2 * i] * uu[2 * i] + w1[2 * i] * u1[2 * i] + w2[2 * i] * u2[2 * i]);
;                         cv[2 * i + 1] = bf_hi(gb[i]) * (w0[2 * i + 1] * uu[2 * i + 1] + w1[2 * i + 1] * u1[2 * i + 1] + w2[2 * i + 1] * u2[2 * i + 1]);
;                     }
; #pragma unroll
;                     for (int i = 0; i < 8; ++i) { ss += cv[i] * cv[i]; u2[i] = u1[i]; u1[i] = uu[i]; }
;                     ss = wave_sum(ss);
;                     const float rc = rsqrtf(ss * (1.0f / 512.0f) + EPS);
;                     u32x4 oc;
; #pragma unroll
;                     for (int i = 0; i < 4; ++i) oc[i] = cvt_pk_bf16(cv[2 * i] * rc, cv[2 * i + 1] * rc);
;                     *(u32x4*)(MIX + (size_t)r * 1024 + 512 + c0) = oc;
;                     u32x2 pw; pw.x = cvt_pk_bf16(pv4[0], pv4[1]); pw.y = cvt_pk_bf16(pv4[2], pv4[3]);
;                     *(u32x2*)(PB + (size_t)r * PLE + lane * 4) = pw;
;                 }
	v_lshlrev_b32_e32 v204, 16, v18
	v_and_b32_e32 v205, 0xffff0000, v18
	v_lshlrev_b32_e32 v206, 16, v19
	v_and_b32_e32 v207, 0xffff0000, v19
	v_lshlrev_b32_e32 v208, 16, v20
	v_and_b32_e32 v209, 0xffff0000, v20
	v_lshlrev_b32_e32 v210, 16, v21
	v_and_b32_e32 v211, 0xffff0000, v21
	v_mul_f32_e32 v140, v164, v204
	v_mul_f32_e32 v141, v165, v205
	v_mul_f32_e32 v142, v166, v206
	v_mul_f32_e32 v143, v167, v207
	v_mul_f32_e32 v144, v168, v208
	v_mul_f32_e32 v145, v169, v209
	v_mul_f32_e32 v146, v170, v210
	v_mul_f32_e32 v147, v171, v211
	v_fmac_f32_e32 v140, v172, v196
	v_fmac_f32_e32 v141, v173, v197
	v_fmac_f32_e32 v142, v174, v198
	v_fmac_f32_e32 v143, v175, v199
	v_fmac_f32_e32 v144, v176, v200
	v_fmac_f32_e32 v145, v177, v201
	v_fmac_f32_e32 v146, v178, v202
	v_fmac_f32_e32 v147, v179, v203
	v_fmac_f32_e32 v140, v180, v188
	v_fmac_f32_e32 v141, v181, v189
	v_fmac_f32_e32 v142, v182, v190
	v_fmac_f32_e32 v143, v183, v191
	v_fmac_f32_e32 v144, v184, v192
	v_fmac_f32_e32 v145, v185, v193
	v_fmac_f32_e32 v146, v186, v194
	v_fmac_f32_e32 v147, v187, v195
	v_lshlrev_b32_e32 v150, 16, v2
	v_and_b32_e32 v151, 0xffff0000, v2
	v_mul_f32_e32 v140, v150, v140
	v_mul_f32_e32 v141, v151, v141
	v_lshlrev_b32_e32 v150, 16, v3
	v_and_b32_e32 v151, 0xffff0000, v3
	v_mul_f32_e32 v142, v150, v142
	v_mul_f32_e32 v143, v151, v143
	v_lshlrev_b32_e32 v150, 16, v4
	v_and_b32_e32 v151, 0xffff0000, v4
	v_mul_f32_e32 v144, v150, v144
	v_mul_f32_e32 v145, v151, v145
	v_lshlrev_b32_e32 v150, 16, v5
	v_and_b32_e32 v151, 0xffff0000, v5
	v_mul_f32_e32 v146, v150, v146
	v_mul_f32_e32 v147, v151, v147
	v_mul_f32_e32 v148, v140, v140
	v_fmac_f32_e32 v148, v141, v141
	v_fmac_f32_e32 v148, v142, v142
	v_fmac_f32_e32 v148, v143, v143
	v_fmac_f32_e32 v148, v144, v144
	v_fmac_f32_e32 v148, v145, v145
	v_fmac_f32_e32 v148, v146, v146
	v_fmac_f32_e32 v148, v147, v147
	v_cvt_pk_bf16_f32 v150, v34, v35
	v_cvt_pk_bf16_f32 v151, v36, v37
	global_store_dwordx2 v[158:159], v[150:151], off
	v_mad_i64_i32 v[152:153], vcc, s41, v221, v[58:59]
	s_add_u32 s41, s41, 1
	global_load_dwordx4 v[2:5], v[152:153], off offset:1536
	global_load_dwordx4 v[18:21], v[152:153], off offset:2560
	global_load_dwordx4 v[34:37], v[154:155], off
	ds_bpermute_b32 v150, v80, v148
	s_waitcnt lgkmcnt(0)
	v_add_f32_e32 v148, v148, v150
	ds_bpermute_b32 v150, v81, v148
	s_waitcnt lgkmcnt(0)
	v_add_f32_e32 v148, v148, v150
	ds_bpermute_b32 v150, v82, v148
	s_waitcnt lgkmcnt(0)
	v_add_f32_e32 v148, v148, v150
	ds_bpermute_b32 v150, v83, v148
	s_waitcnt lgkmcnt(0)
	v_add_f32_e32 v148, v148, v150
	ds_bpermute_b32 v150, v84, v148
	s_waitcnt lgkmcnt(0)
	v_add_f32_e32 v148, v148, v150
	ds_bpermute_b32 v150, v85, v148
	s_waitcnt lgkmcnt(0)
	v_add_f32_e32 v148, v148, v150
	v_fmamk_f32 v148, v148, 0x3b000000, v162
	v_mul_f32_e32 v150, 0x4b800000, v148
	v_cmp_gt_f32_e32 vcc, s31, v148
	s_nop 1
	v_cndmask_b32_e32 v148, v148, v150, vcc
	v_rsq_f32_e32 v148, v148
	s_nop 0
	v_mul_f32_e32 v150, 0x45800000, v148
	v_cndmask_b32_e32 v149, v148, v150, vcc
	v_mul_f32_e32 v140, v149, v140
	v_mul_f32_e32 v141, v149, v141
	v_mul_f32_e32 v142, v149, v142
	v_mul_f32_e32 v143, v149, v143
	v_mul_f32_e32 v144, v149, v144
	v_mul_f32_e32 v145, v149, v145
	v_mul_f32_e32 v146, v149, v146
	v_mul_f32_e32 v147, v149, v147
	v_cvt_pk_bf16_f32 v140, v140, v141
	v_cvt_pk_bf16_f32 v141, v142, v143
	v_cvt_pk_bf16_f32 v142, v144, v145
	v_cvt_pk_bf16_f32 v143, v146, v147
	global_store_dwordx4 v[156:157], v[140:143], off
	s_waitcnt vmcnt(16)
	v_lshlrev_b32_e32 v188, 16, v22
	v_and_b32_e32 v189, 0xffff0000, v22
	v_lshlrev_b32_e32 v190, 16, v23
	v_and_b32_e32 v191, 0xffff0000, v23
	v_lshlrev_b32_e32 v192, 16, v24
	v_and_b32_e32 v193, 0xffff0000, v24
	v_lshlrev_b32_e32 v194, 16, v25
	v_and_b32_e32 v195, 0xffff0000, v25
	v_mul_f32_e32 v140, v164, v188
	v_mul_f32_e32 v141, v165, v189
	v_mul_f32_e32 v142, v166, v190
	v_mul_f32_e32 v143, v167, v191
	v_mul_f32_e32 v144, v168, v192
	v_mul_f32_e32 v145, v169, v193
	v_mul_f32_e32 v146, v170, v194
	v_mul_f32_e32 v147, v171, v195
	v_fmac_f32_e32 v140, v172, v204
	v_fmac_f32_e32 v141, v173, v205
	v_fmac_f32_e32 v142, v174, v206
	v_fmac_f32_e32 v143, v175, v207
	v_fmac_f32_e32 v144, v176, v208
	v_fmac_f32_e32 v145, v177, v209
	v_fmac_f32_e32 v146, v178, v210
	v_fmac_f32_e32 v147, v179, v211
	v_fmac_f32_e32 v140, v180, v196
	v_fmac_f32_e32 v141, v181, v197
	v_fmac_f32_e32 v142, v182, v198
	v_fmac_f32_e32 v143, v183, v199
	v_fmac_f32_e32 v144, v184, v200
	v_fmac_f32_e32 v145, v185, v201
	v_fmac_f32_e32 v146, v186, v202
	v_fmac_f32_e32 v147, v187, v203
	v_lshlrev_b32_e32 v150, 16, v6
	v_and_b32_e32 v151, 0xffff0000, v6
	v_mul_f32_e32 v140, v150, v140
	v_mul_f32_e32 v141, v151, v141
	v_lshlrev_b32_e32 v150, 16, v7
	v_and_b32_e32 v151, 0xffff0000, v7
	v_mul_f32_e32 v142, v150, v142
	v_mul_f32_e32 v143, v151, v143
	v_lshlrev_b32_e32 v150, 16, v8
	v_and_b32_e32 v151, 0xffff0000, v8
	v_mul_f32_e32 v144, v150, v144
	v_mul_f32_e32 v145, v151, v145
	v_lshlrev_b32_e32 v150, 16, v9
	v_and_b32_e32 v151, 0xffff0000, v9
	v_mul_f32_e32 v146, v150, v146
	v_mul_f32_e32 v147, v151, v147
	v_mul_f32_e32 v148, v140, v140
	v_fmac_f32_e32 v148, v141, v141
	v_fmac_f32_e32 v148, v142, v142
	v_fmac_f32_e32 v148, v143, v143
	v_fmac_f32_e32 v148, v144, v144
	v_fmac_f32_e32 v148, v145, v145
	v_fmac_f32_e32 v148, v146, v146
	v_fmac_f32_e32 v148, v147, v147
	v_cvt_pk_bf16_f32 v150, v38, v39
	v_cvt_pk_bf16_f32 v151, v40, v41
	global_store_dwordx2 v[158:159], v[150:151], off offset:512
	v_mad_i64_i32 v[152:153], vcc, s41, v221, v[58:59]
	s_add_u32 s41, s41, 1
	global_load_dwordx4 v[6:9], v[152:153], off offset:1536
	global_load_dwordx4 v[22:25], v[152:153], off offset:2560
	global_load_dwordx4 v[38:41], v[154:155], off offset:1024
	ds_bpermute_b32 v150, v80, v148
	s_waitcnt lgkmcnt(0)
; __device__ __forceinline__ unsigned cvt_pk_bf16(float lo, float hi) { unsigned r; asm volatile("v_cvt_pk_bf16_f32 %0, %1, %2" : "=v"(r) : "v"(lo), "v"(hi)); return r; }
; __device__ __forceinline__ float bf_lo(unsigned w) { return __uint_as_float(w << 16); }
; __device__ __forceinline__ float bf_hi(unsigned w) { return __uint_as_float(w & 0xffff0000u); }
; __global__ void __launch_bounds__(512, 2) trunk_fwd(Args args) {
;     ...
;                     float cv[8], uu[8]; float ss = 0.f;
; #pragma unroll
;                     for (int i = 0; i < 4; ++i) {
;                         uu[2 * i] = bf_lo(gu[i]); uu[2 * i + 1] = bf_hi(gu[i]);
;                         cv[2 * i] = bf_lo(gb[i]) * (w0[2 * i] * uu[2 * i] + w1[2 * i] * u1[2 * i] + w2[2 * i] * u2[2 * i]);
;                         cv[2 * i + 1] = bf_hi(gb[i]) * (w0[2 * i + 1] * uu[2 * i + 1] + w1[2 * i + 1] * u1[2 * i + 1] + w2[2 * i + 1] * u2[2 * i + 1]);
;                     }
; #pragma unroll
;                     for (int i = 0; i < 8; ++i) { ss += cv[i] * cv[i]; u2[i] = u1[i]; u1[i] = uu[i]; }
;                     ss = wave_sum(ss);
;                     const float rc = rsqrtf(ss * (1.0f / 512.0f) + EPS);
;                     u32x4 oc;
; #pragma unroll
;                     for (int i = 0; i < 4; ++i) oc[i] = cvt_pk_bf16(cv[2 * i] * rc, cv[2 * i + 1] * rc);
;                     *(u32x4*)(MIX + (size_t)r * 1024 + 512 + c0) = oc;
;                     u32x2 pw; pw.x = cvt_pk_bf16(pv4[0], pv4[1]); pw.y = cvt_pk_bf16(pv4[2], pv4[3]);
;                     *(u32x2*)(PB + (size_t)r * PLE + lane * 4) = pw;
;                 }
	v_add_f32_e32 v148, v148, v150
	ds_bpermute_b32 v150, v81, v148
	s_waitcnt lgkmcnt(0)
	v_add_f32_e32 v148, v148, v150
	ds_bpermute_b32 v150, v82, v148
	s_waitcnt lgkmcnt(0)
	v_add_f32_e32 v148, v148, v150
	ds_bpermute_b32 v150, v83, v148
	s_waitcnt lgkmcnt(0)
	v_add_f32_e32 v148, v148, v150
	ds_bpermute_b32 v150, v84, v148
	s_waitcnt lgkmcnt(0)
	v_add_f32_e32 v148, v148, v150
	ds_bpermute_b32 v150, v85, v148
	s_waitcnt lgkmcnt(0)
	v_add_f32_e32 v148, v148, v150
	v_fmamk_f32 v148, v148, 0x3b000000, v162
	v_mul_f32_e32 v150, 0x4b800000, v148
	v_cmp_gt_f32_e32 vcc, s31, v148
	s_nop 1
	v_cndmask_b32_e32 v148, v148, v150, vcc
	v_rsq_f32_e32 v148, v148
	s_nop 0
	v_mul_f32_e32 v150, 0x45800000, v148
	v_cndmask_b32_e32 v149, v148, v150, vcc
	v_mul_f32_e32 v140, v149, v140
	v_mul_f32_e32 v141, v149, v141
	v_mul_f32_e32 v142, v149, v142
	v_mul_f32_e32 v143, v149, v143
	v_mul_f32_e32 v144, v149, v144
	v_mul_f32_e32 v145, v149, v145
	v_mul_f32_e32 v146, v149, v146
	v_mul_f32_e32 v147, v149, v147
	v_cvt_pk_bf16_f32 v140, v140, v141
	v_cvt_pk_bf16_f32 v141, v142, v143
	v_cvt_pk_bf16_f32 v142, v144, v145
	v_cvt_pk_bf16_f32 v143, v146, v147
	global_store_dwordx4 v[156:157], v[140:143], off offset:2048
	v_lshl_add_u64 v[156:157], v[156:157], 0, s[20:21]
	s_waitcnt vmcnt(16)
	v_lshlrev_b32_e32 v196, 16, v26
	v_and_b32_e32 v197, 0xffff0000, v26
	v_lshlrev_b32_e32 v198, 16, v27
	v_and_b32_e32 v199, 0xffff0000, v27
	v_lshlrev_b32_e32 v200, 16, v28
	v_and_b32_e32 v201, 0xffff0000, v28
	v_lshlrev_b32_e32 v202, 16, v29
	v_and_b32_e32 v203, 0xffff0000, v29
	v_mul_f32_e32 v140, v164, v196
	v_mul_f32_e32 v141, v165, v197
	v_mul_f32_e32 v142, v166, v198
	v_mul_f32_e32 v143, v167, v199
	v_mul_f32_e32 v144, v168, v200
	v_mul_f32_e32 v145, v169, v201
	v_mul_f32_e32 v146, v170, v202
	v_mul_f32_e32 v147, v171, v203
	v_fmac_f32_e32 v140, v172, v188
	v_fmac_f32_e32 v141, v173, v189
	v_fmac_f32_e32 v142, v174, v190
	v_fmac_f32_e32 v143, v175, v191
	v_fmac_f32_e32 v144, v176, v192
	v_fmac_f32_e32 v145, v177, v193
	v_fmac_f32_e32 v146, v178, v194
	v_fmac_f32_e32 v147, v179, v195
	v_fmac_f32_e32 v140, v180, v204
	v_fmac_f32_e32 v141, v181, v205
	v_fmac_f32_e32 v142, v182, v206
	v_fmac_f32_e32 v143, v183, v207
	v_fmac_f32_e32 v144, v184, v208
	v_fmac_f32_e32 v145, v185, v209
	v_fmac_f32_e32 v146, v186, v210
	v_fmac_f32_e32 v147, v187, v211
	v_lshlrev_b32_e32 v150, 16, v10
	v_and_b32_e32 v151, 0xffff0000, v10
	v_mul_f32_e32 v140, v150, v140
	v_mul_f32_e32 v141, v151, v141
	v_lshlrev_b32_e32 v150, 16, v11
	v_and_b32_e32 v151, 0xffff0000, v11
	v_mul_f32_e32 v142, v150, v142
	v_mul_f32_e32 v143, v151, v143
	v_lshlrev_b32_e32 v150, 16, v12
	v_and_b32_e32 v151, 0xffff0000, v12
	v_mul_f32_e32 v144, v150, v144
	v_mul_f32_e32 v145, v151, v145
	v_lshlrev_b32_e32 v150, 16, v13
	v_and_b32_e32 v151, 0xffff0000, v13
	v_mul_f32_e32 v146, v150, v146
	v_mul_f32_e32 v147, v151, v147
	v_mul_f32_e32 v148, v140, v140
	v_fmac_f32_e32 v148, v141, v141
	v_fmac_f32_e32 v148, v142, v142
	v_fmac_f32_e32 v148, v143, v143
	v_fmac_f32_e32 v148, v144, v144
	v_fmac_f32_e32 v148, v145, v145
	v_fmac_f32_e32 v148, v146, v146
	v_fmac_f32_e32 v148, v147, v147
	v_cvt_pk_bf16_f32 v150, v42, v43
	v_cvt_pk_bf16_f32 v151, v44, v45
	global_store_dwordx2 v[158:159], v[150:151], off offset:1024
	v_mad_i64_i32 v[152:153], vcc, s41, v221, v[58:59]
	s_add_u32 s41, s41, 1
	global_load_dwordx4 v[10:13], v[152:153], off offset:1536
	global_load_dwordx4 v[26:29], v[152:153], off offset:2560
	global_load_dwordx4 v[42:45], v[154:155], off offset:2048
	ds_bpermute_b32 v150, v80, v148
	s_waitcnt lgkmcnt(0)
	v_add_f32_e32 v148, v148, v150
	ds_bpermute_b32 v150, v81, v148
	s_waitcnt lgkmcnt(0)
	v_add_f32_e32 v148, v148, v150
	ds_bpermute_b32 v150, v82, v148
	s_waitcnt lgkmcnt(0)
	v_add_f32_e32 v148, v148, v150
	ds_bpermute_b32 v150, v83, v148
	s_waitcnt lgkmcnt(0)
	v_add_f32_e32 v148, v148, v150
	ds_bpermute_b32 v150, v84, v148
	s_waitcnt lgkmcnt(0)
	v_add_f32_e32 v148, v148, v150
	ds_bpermute_b32 v150, v85, v148
	s_waitcnt lgkmcnt(0)
	v_add_f32_e32 v148, v148, v150
	v_fmamk_f32 v148, v148, 0x3b000000, v162
	v_mul_f32_e32 v150, 0x4b800000, v148
	v_cmp_gt_f32_e32 vcc, s31, v148
	s_nop 1
	v_cndmask_b32_e32 v148, v148, v150, vcc
	v_rsq_f32_e32 v148, v148
	s_nop 0
	v_mul_f32_e32 v150, 0x45800000, v148
	v_cndmask_b32_e32 v149, v148, v150, vcc
	v_mul_f32_e32 v140, v149, v140
	v_mul_f32_e32 v141, v149, v141
	v_mul_f32_e32 v142, v149, v142
	v_mul_f32_e32 v143, v149, v143
	v_mul_f32_e32 v144, v149, v144
	v_mul_f32_e32 v145, v149, v145
	v_mul_f32_e32 v146, v149, v146
	v_mul_f32_e32 v147, v149, v147
	v_cvt_pk_bf16_f32 v140, v140, v141
	v_cvt_pk_bf16_f32 v141, v142, v143
	v_cvt_pk_bf16_f32 v142, v144, v145
	v_cvt_pk_bf16_f32 v143, v146, v147
	global_store_dwordx4 v[156:157], v[140:143], off
	s_waitcnt vmcnt(16)
; __device__ __forceinline__ unsigned cvt_pk_bf16(float lo, float hi) { unsigned r; asm volatile("v_cvt_pk_bf16_f32 %0, %1, %2" : "=v"(r) : "v"(lo), "v"(hi)); return r; }
; __device__ __forceinline__ float bf_lo(unsigned w) { return __uint_as_float(w << 16); }
; __device__ __forceinline__ float bf_hi(unsigned w) { return __uint_as_float(w & 0xffff0000u); }
; __global__ void __launch_bounds__(512, 2) trunk_fwd(Args args) {
;     ...
;                     float cv[8], uu[8]; float ss = 0.f;
; #pragma unroll
;                     for (int i = 0; i < 4; ++i) {
;                         uu[2 * i] = bf_lo(gu[i]); uu[2 * i + 1] = bf_hi(gu[i]);
;                         cv[2 * i] = bf_lo(gb[i]) * (w0[2 * i] * uu[2 * i] + w1[2 * i] * u1[2 * i] + w2[2 * i] * u2[2 * i]);
;                         cv[2 * i + 1] = bf_hi(gb[i]) * (w0[2 * i + 1] * uu[2 * i + 1] + w1[2 * i + 1] * u1[2 * i + 1] + w2[2 * i + 1] * u2[2 * i + 1]);
;                     }
; #pragma unroll
;                     for (int i = 0; i < 8; ++i) { ss += cv[i] * cv[i]; u2[i] = u1[i]; u1[i] = uu[i]; }
;                     ss = wave_sum(ss);
;                     const float rc = rsqrtf(ss * (1.0f / 512.0f) + EPS);
;                     u32x4 oc;
; #pragma unroll
;                     for (int i = 0; i < 4; ++i) oc[i] = cvt_pk_bf16(cv[2 * i] * rc, cv[2 * i + 1] * rc);
;                     *(u32x4*)(MIX + (size_t)r * 1024 + 512 + c0) = oc;
;                     u32x2 pw; pw.x = cvt_pk_bf16(pv4[0], pv4[1]); pw.y = cvt_pk_bf16(pv4[2], pv4[3]);
;                     *(u32x2*)(PB + (size_t)r * PLE + lane * 4) = pw;
;                 }
	v_lshlrev_b32_e32 v204, 16, v30
	v_and_b32_e32 v205, 0xffff0000, v30
	v_lshlrev_b32_e32 v206, 16, v31
	v_and_b32_e32 v207, 0xffff0000, v31
	v_lshlrev_b32_e32 v208, 16, v32
	v_and_b32_e32 v209, 0xffff0000, v32
	v_lshlrev_b32_e32 v210, 16, v33
	v_and_b32_e32 v211, 0xffff0000, v33
	v_mul_f32_e32 v140, v164, v204
	v_mul_f32_e32 v141, v165, v205
	v_mul_f32_e32 v142, v166, v206
	v_mul_f32_e32 v143, v167, v207
	v_mul_f32_e32 v144, v168, v208
	v_mul_f32_e32 v145, v169, v209
	v_mul_f32_e32 v146, v170, v210
	v_mul_f32_e32 v147, v171, v211
	v_fmac_f32_e32 v140, v172, v196
	v_fmac_f32_e32 v141, v173, v197
	v_fmac_f32_e32 v142, v174, v198
	v_fmac_f32_e32 v143, v175, v199
	v_fmac_f32_e32 v144, v176, v200
	v_fmac_f32_e32 v145, v177, v201
	v_fmac_f32_e32 v146, v178, v202
	v_fmac_f32_e32 v147, v179, v203
	v_fmac_f32_e32 v140, v180, v188
	v_fmac_f32_e32 v141, v181, v189
	v_fmac_f32_e32 v142, v182, v190
	v_fmac_f32_e32 v143, v183, v191
	v_fmac_f32_e32 v144, v184, v192
	v_fmac_f32_e32 v145, v185, v193
	v_fmac_f32_e32 v146, v186, v194
	v_fmac_f32_e32 v147, v187, v195
	v_lshlrev_b32_e32 v150, 16, v14
	v_and_b32_e32 v151, 0xffff0000, v14
	v_mul_f32_e32 v140, v150, v140
	v_mul_f32_e32 v141, v151, v141
	v_lshlrev_b32_e32 v150, 16, v15
	v_and_b32_e32 v151, 0xffff0000, v15
	v_mul_f32_e32 v142, v150, v142
	v_mul_f32_e32 v143, v151, v143
	v_lshlrev_b32_e32 v150, 16, v16
	v_and_b32_e32 v151, 0xffff0000, v16
	v_mul_f32_e32 v144, v150, v144
	v_mul_f32_e32 v145, v151, v145
	v_lshlrev_b32_e32 v150, 16, v17
	v_and_b32_e32 v151, 0xffff0000, v17
	v_mul_f32_e32 v146, v150, v146
	v_mul_f32_e32 v147, v151, v147
	v_mul_f32_e32 v148, v140, v140
	v_fmac_f32_e32 v148, v141, v141
	v_fmac_f32_e32 v148, v142, v142
	v_fmac_f32_e32 v148, v143, v143
	v_fmac_f32_e32 v148, v144, v144
	v_fmac_f32_e32 v148, v145, v145
	v_fmac_f32_e32 v148, v146, v146
	v_fmac_f32_e32 v148, v147, v147
	v_cvt_pk_bf16_f32 v150, v46, v47
	v_cvt_pk_bf16_f32 v151, v48, v49
	global_store_dwordx2 v[158:159], v[150:151], off offset:1536
	v_mad_i64_i32 v[152:153], vcc, s41, v221, v[58:59]
	s_add_u32 s41, s41, 1
	global_load_dwordx4 v[14:17], v[152:153], off offset:1536
	global_load_dwordx4 v[30:33], v[152:153], off offset:2560
	global_load_dwordx4 v[46:49], v[154:155], off offset:3072
	v_lshl_add_u64 v[154:155], v[154:155], 0, s[20:21]
	ds_bpermute_b32 v150, v80, v148
	s_waitcnt lgkmcnt(0)
	v_add_f32_e32 v148, v148, v150
	ds_bpermute_b32 v150, v81, v148
	s_waitcnt lgkmcnt(0)
	v_add_f32_e32 v148, v148, v150
	ds_bpermute_b32 v150, v82, v148
	s_waitcnt lgkmcnt(0)
	v_add_f32_e32 v148, v148, v150
	ds_bpermute_b32 v150, v83, v148
	s_waitcnt lgkmcnt(0)
	v_add_f32_e32 v148, v148, v150
	ds_bpermute_b32 v150, v84, v148
	s_waitcnt lgkmcnt(0)
	v_add_f32_e32 v148, v148, v150
	ds_bpermute_b32 v150, v85, v148
	s_waitcnt lgkmcnt(0)
	v_add_f32_e32 v148, v148, v150
	v_fmamk_f32 v148, v148, 0x3b000000, v162
	v_mul_f32_e32 v150, 0x4b800000, v148
	v_cmp_gt_f32_e32 vcc, s31, v148
	s_nop 1
	v_cndmask_b32_e32 v148, v148, v150, vcc
	v_rsq_f32_e32 v148, v148
	s_nop 0
	v_mul_f32_e32 v150, 0x45800000, v148
	v_cndmask_b32_e32 v149, v148, v150, vcc
	v_mul_f32_e32 v140, v149, v140
	v_mul_f32_e32 v141, v149, v141
	v_mul_f32_e32 v142, v149, v142
	v_mul_f32_e32 v143, v149, v143
	v_mul_f32_e32 v144, v149, v144
	v_mul_f32_e32 v145, v149, v145
	v_mul_f32_e32 v146, v149, v146
	v_mul_f32_e32 v147, v149, v147
	v_cvt_pk_bf16_f32 v140, v140, v141
	v_cvt_pk_bf16_f32 v141, v142, v143
	v_cvt_pk_bf16_f32 v142, v144, v145
	v_cvt_pk_bf16_f32 v143, v146, v147
	global_store_dwordx4 v[156:157], v[140:143], off offset:2048
	v_lshl_add_u64 v[156:157], v[156:157], 0, s[20:21]
	s_waitcnt vmcnt(16)
	v_lshlrev_b32_e32 v188, 16, v18
	v_and_b32_e32 v189, 0xffff0000, v18
	v_lshlrev_b32_e32 v190, 16, v19
	v_and_b32_e32 v191, 0xffff0000, v19
	v_lshlrev_b32_e32 v192, 16, v20
	v_and_b32_e32 v193, 0xffff0000, v20
	v_lshlrev_b32_e32 v194, 16, v21
	v_and_b32_e32 v195, 0xffff0000, v21
	v_mul_f32_e32 v140, v164, v188
	v_mul_f32_e32 v141, v165, v189
	v_mul_f32_e32 v142, v166, v190
	v_mul_f32_e32 v143, v167, v191
	v_mul_f32_e32 v144, v168, v192
	v_mul_f32_e32 v145, v169, v193
	v_mul_f32_e32 v146, v170, v194
	v_mul_f32_e32 v147, v171, v195
	v_fmac_f32_e32 v140, v172, v204
	v_fmac_f32_e32 v141, v173, v205
	v_fmac_f32_e32 v142, v174, v206
	v_fmac_f32_e32 v143, v175, v207
	v_fmac_f32_e32 v144, v176, v208
	v_fmac_f32_e32 v145, v177, v209
	v_fmac_f32_e32 v146, v178, v210
	v_fmac_f32_e32 v147, v179, v211
	v_fmac_f32_e32 v140, v180, v196
	v_fmac_f32_e32 v141, v181, v197
	v_fmac_f32_e32 v142, v182, v198
	v_fmac_f32_e32 v143, v183, v199
	v_fmac_f32_e32 v144, v184, v200
	v_fmac_f32_e32 v145, v185, v201
	v_fmac_f32_e32 v146, v186, v202
	v_fmac_f32_e32 v147, v187, v203
	v_lshlrev_b32_e32 v150, 16, v2
	v_and_b32_e32 v151, 0xffff0000, v2
	v_mul_f32_e32 v140, v150, v140
	v_mul_f32_e32 v141, v151, v141
	v_lshlrev_b32_e32 v150, 16, v3
	v_and_b32_e32 v151, 0xffff0000, v3
	v_mul_f32_e32 v142, v150, v142
	v_mul_f32_e32 v143, v151, v143
	v_lshlrev_b32_e32 v150, 16, v4
	v_and_b32_e32 v151, 0xffff0000, v4
	v_mul_f32_e32 v144, v150, v144
	v_mul_f32_e32 v145, v151, v145
	v_lshlrev_b32_e32 v150, 16, v5
	v_and_b32_e32 v151, 0xffff0000, v5
	v_mul_f32_e32 v146, v150, v146
	v_mul_f32_e32 v147, v151, v147
	v_mul_f32_e32 v148, v140, v140
	v_fmac_f32_e32 v148, v141, v141
	v_fmac_f32_e32 v148, v142, v142
	v_fmac_f32_e32 v148, v143, v143
	v_fmac_f32_e32 v148, v144, v144
	v_fmac_f32_e32 v148, v145, v145
	v_fmac_f32_e32 v148, v146, v146
	v_fmac_f32_e32 v148, v147, v147
	v_cvt_pk_bf16_f32 v150, v34, v35
	v_cvt_pk_bf16_f32 v151, v36, v37
	global_store_dwordx2 v[158:159], v[150:151], off offset:2048
	ds_bpermute_b32 v150, v80, v148
	s_waitcnt lgkmcnt(0)
; __device__ __forceinline__ unsigned cvt_pk_bf16(float lo, float hi) { unsigned r; asm volatile("v_cvt_pk_bf16_f32 %0, %1, %2" : "=v"(r) : "v"(lo), "v"(hi)); return r; }
; __device__ __forceinline__ float bf_lo(unsigned w) { return __uint_as_float(w << 16); }
; __device__ __forceinline__ float bf_hi(unsigned w) { return __uint_as_float(w & 0xffff0000u); }
; __global__ void __launch_bounds__(512, 2) trunk_fwd(Args args) {
;     ...
;                     float cv[8], uu[8]; float ss = 0.f;
; #pragma unroll
;                     for (int i = 0; i < 4; ++i) {
;                         uu[2 * i] = bf_lo(gu[i]); uu[2 * i + 1] = bf_hi(gu[i]);
;                         cv[2 * i] = bf_lo(gb[i]) * (w0[2 * i] * uu[2 * i] + w1[2 * i] * u1[2 * i] + w2[2 * i] * u2[2 * i]);
;                         cv[2 * i + 1] = bf_hi(gb[i]) * (w0[2 * i + 1] * uu[2 * i + 1] + w1[2 * i + 1] * u1[2 * i + 1] + w2[2 * i + 1] * u2[2 * i + 1]);
;                     }
; #pragma unroll
;                     for (int i = 0; i < 8; ++i) { ss += cv[i] * cv[i]; u2[i] = u1[i]; u1[i] = uu[i]; }
;                     ss = wave_sum(ss);
;                     const float rc = rsqrtf(ss * (1.0f / 512.0f) + EPS);
;                     u32x4 oc;
; #pragma unroll
;                     for (int i = 0; i < 4; ++i) oc[i] = cvt_pk_bf16(cv[2 * i] * rc, cv[2 * i + 1] * rc);
;                     *(u32x4*)(MIX + (size_t)r * 1024 + 512 + c0) = oc;
;                     u32x2 pw; pw.x = cvt_pk_bf16(pv4[0], pv4[1]); pw.y = cvt_pk_bf16(pv4[2], pv4[3]);
;                     *(u32x2*)(PB + (size_t)r * PLE + lane * 4) = pw;
;                 }
	v_add_f32_e32 v148, v148, v150
	ds_bpermute_b32 v150, v81, v148
	s_waitcnt lgkmcnt(0)
	v_add_f32_e32 v148, v148, v150
	ds_bpermute_b32 v150, v82, v148
	s_waitcnt lgkmcnt(0)
	v_add_f32_e32 v148, v148, v150
	ds_bpermute_b32 v150, v83, v148
	s_waitcnt lgkmcnt(0)
	v_add_f32_e32 v148, v148, v150
	ds_bpermute_b32 v150, v84, v148
	s_waitcnt lgkmcnt(0)
	v_add_f32_e32 v148, v148, v150
	ds_bpermute_b32 v150, v85, v148
	s_waitcnt lgkmcnt(0)
	v_add_f32_e32 v148, v148, v150
	v_fmamk_f32 v148, v148, 0x3b000000, v162
	v_mul_f32_e32 v150, 0x4b800000, v148
	v_cmp_gt_f32_e32 vcc, s31, v148
	s_nop 1
	v_cndmask_b32_e32 v148, v148, v150, vcc
	v_rsq_f32_e32 v148, v148
	s_nop 0
	v_mul_f32_e32 v150, 0x45800000, v148
	v_cndmask_b32_e32 v149, v148, v150, vcc
	v_mul_f32_e32 v140, v149, v140
	v_mul_f32_e32 v141, v149, v141
	v_mul_f32_e32 v142, v149, v142
	v_mul_f32_e32 v143, v149, v143
	v_mul_f32_e32 v144, v149, v144
	v_mul_f32_e32 v145, v149, v145
	v_mul_f32_e32 v146, v149, v146
	v_mul_f32_e32 v147, v149, v147
	v_cvt_pk_bf16_f32 v140, v140, v141
	v_cvt_pk_bf16_f32 v141, v142, v143
	v_cvt_pk_bf16_f32 v142, v144, v145
	v_cvt_pk_bf16_f32 v143, v146, v147
	global_store_dwordx4 v[156:157], v[140:143], off
	s_waitcnt vmcnt(13)
	v_lshlrev_b32_e32 v196, 16, v22
	v_and_b32_e32 v197, 0xffff0000, v22
	v_lshlrev_b32_e32 v198, 16, v23
	v_and_b32_e32 v199, 0xffff0000, v23
	v_lshlrev_b32_e32 v200, 16, v24
	v_and_b32_e32 v201, 0xffff0000, v24
	v_lshlrev_b32_e32 v202, 16, v25
	v_and_b32_e32 v203, 0xffff0000, v25
	v_mul_f32_e32 v140, v164, v196
	v_mul_f32_e32 v141, v165, v197
	v_mul_f32_e32 v142, v166, v198
	v_mul_f32_e32 v143, v167, v199
	v_mul_f32_e32 v144, v168, v200
	v_mul_f32_e32 v145, v169, v201
	v_mul_f32_e32 v146, v170, v202
	v_mul_f32_e32 v147, v171, v203
	v_fmac_f32_e32 v140, v172, v188
	v_fmac_f32_e32 v141, v173, v189
	v_fmac_f32_e32 v142, v174, v190
	v_fmac_f32_e32 v143, v175, v191
	v_fmac_f32_e32 v144, v176, v192
	v_fmac_f32_e32 v145, v177, v193
	v_fmac_f32_e32 v146, v178, v194
	v_fmac_f32_e32 v147, v179, v195
	v_fmac_f32_e32 v140, v180, v204
	v_fmac_f32_e32 v141, v181, v205
	v_fmac_f32_e32 v142, v182, v206
	v_fmac_f32_e32 v143, v183, v207
	v_fmac_f32_e32 v144, v184, v208
	v_fmac_f32_e32 v145, v185, v209
	v_fmac_f32_e32 v146, v186, v210
	v_fmac_f32_e32 v147, v187, v211
	v_lshlrev_b32_e32 v150, 16, v6
	v_and_b32_e32 v151, 0xffff0000, v6
	v_mul_f32_e32 v140, v150, v140
	v_mul_f32_e32 v141, v151, v141
	v_lshlrev_b32_e32 v150, 16, v7
	v_and_b32_e32 v151, 0xffff0000, v7
	v_mul_f32_e32 v142, v150, v142
	v_mul_f32_e32 v143, v151, v143
	v_lshlrev_b32_e32 v150, 16, v8
	v_and_b32_e32 v151, 0xffff0000, v8
	v_mul_f32_e32 v144, v150, v144
	v_mul_f32_e32 v145, v151, v145
	v_lshlrev_b32_e32 v150, 16, v9
	v_and_b32_e32 v151, 0xffff0000, v9
	v_mul_f32_e32 v146, v150, v146
	v_mul_f32_e32 v147, v151, v147
	v_mul_f32_e32 v148, v140, v140
	v_fmac_f32_e32 v148, v141, v141
	v_fmac_f32_e32 v148, v142, v142
	v_fmac_f32_e32 v148, v143, v143
	v_fmac_f32_e32 v148, v144, v144
	v_fmac_f32_e32 v148, v145, v145
	v_fmac_f32_e32 v148, v146, v146
	v_fmac_f32_e32 v148, v147, v147
	v_cvt_pk_bf16_f32 v150, v38, v39
	v_cvt_pk_bf16_f32 v151, v40, v41
	global_store_dwordx2 v[158:159], v[150:151], off offset:2560
	ds_bpermute_b32 v150, v80, v148
	s_waitcnt lgkmcnt(0)
	v_add_f32_e32 v148, v148, v150
	ds_bpermute_b32 v150, v81, v148
	s_waitcnt lgkmcnt(0)
	v_add_f32_e32 v148, v148, v150
	ds_bpermute_b32 v150, v82, v148
	s_waitcnt lgkmcnt(0)
	v_add_f32_e32 v148, v148, v150
	ds_bpermute_b32 v150, v83, v148
	s_waitcnt lgkmcnt(0)
	v_add_f32_e32 v148, v148, v150
	ds_bpermute_b32 v150, v84, v148
	s_waitcnt lgkmcnt(0)
	v_add_f32_e32 v148, v148, v150
	ds_bpermute_b32 v150, v85, v148
	s_waitcnt lgkmcnt(0)
	v_add_f32_e32 v148, v148, v150
	v_fmamk_f32 v148, v148, 0x3b000000, v162
	v_mul_f32_e32 v150, 0x4b800000, v148
	v_cmp_gt_f32_e32 vcc, s31, v148
	s_nop 1
	v_cndmask_b32_e32 v148, v148, v150, vcc
	v_rsq_f32_e32 v148, v148
	s_nop 0
	v_mul_f32_e32 v150, 0x45800000, v148
	v_cndmask_b32_e32 v149, v148, v150, vcc
	v_mul_f32_e32 v140, v149, v140
	v_mul_f32_e32 v141, v149, v141
	v_mul_f32_e32 v142, v149, v142
	v_mul_f32_e32 v143, v149, v143
	v_mul_f32_e32 v144, v149, v144
	v_mul_f32_e32 v145, v149, v145
	v_mul_f32_e32 v146, v149, v146
	v_mul_f32_e32 v147, v149, v147
	v_cvt_pk_bf16_f32 v140, v140, v141
	v_cvt_pk_bf16_f32 v141, v142, v143
	v_cvt_pk_bf16_f32 v142, v144, v145
	v_cvt_pk_bf16_f32 v143, v146, v147
	global_store_dwordx4 v[156:157], v[140:143], off offset:2048
	v_lshl_add_u64 v[156:157], v[156:157], 0, s[20:21]
	s_waitcnt vmcnt(10)
	v_lshlrev_b32_e32 v204, 16, v26
	v_and_b32_e32 v205, 0xffff0000, v26
	v_lshlrev_b32_e32 v206, 16, v27
	v_and_b32_e32 v207, 0xffff0000, v27
	v_lshlrev_b32_e32 v208, 16, v28
	v_and_b32_e32 v209, 0xffff0000, v28
	v_lshlrev_b32_e32 v210, 16, v29
	v_and_b32_e32 v211, 0xffff0000, v29
	v_mul_f32_e32 v140, v164, v204
	v_mul_f32_e32 v141, v165, v205
	v_mul_f32_e32 v142, v166, v206
	v_mul_f32_e32 v143, v167, v207
	v_mul_f32_e32 v144, v168, v208
	v_mul_f32_e32 v145, v169, v209
	v_mul_f32_e32 v146, v170, v210
	v_mul_f32_e32 v147, v171, v211
	v_fmac_f32_e32 v140, v172, v196
	v_fmac_f32_e32 v141, v173, v197
	v_fmac_f32_e32 v142, v174, v198
	v_fmac_f32_e32 v143, v175, v199
	v_fmac_f32_e32 v144, v176, v200
	v_fmac_f32_e32 v145, v177, v201
	v_fmac_f32_e32 v146, v178, v202
	v_fmac_f32_e32 v147, v179, v203
	v_fmac_f32_e32 v140, v180, v188
	v_fmac_f32_e32 v141, v181, v189
	v_fmac_f32_e32 v142, v182, v190
	v_fmac_f32_e32 v143, v183, v191
	v_fmac_f32_e32 v144, v184, v192
	v_fmac_f32_e32 v145, v185, v193
	v_fmac_f32_e32 v146, v186, v194
	v_fmac_f32_e32 v147, v187, v195
	v_lshlrev_b32_e32 v150, 16, v10
	v_and_b32_e32 v151, 0xffff0000, v10
	v_mul_f32_e32 v140, v150, v140
	v_mul_f32_e32 v141, v151, v141
	v_lshlrev_b32_e32 v150, 16, v11
	v_and_b32_e32 v151, 0xffff0000, v11
	v_mul_f32_e32 v142, v150, v142
	v_mul_f32_e32 v143, v151, v143
	v_lshlrev_b32_e32 v150, 16, v12
	v_and_b32_e32 v151, 0xffff0000, v12
	v_mul_f32_e32 v144, v150, v144
	v_mul_f32_e32 v145, v151, v145
	v_lshlrev_b32_e32 v150, 16, v13
	v_and_b32_e32 v151, 0xffff0000, v13
	v_mul_f32_e32 v146, v150, v146
	v_mul_f32_e32 v147, v151, v147
	v_mul_f32_e32 v148, v140, v140
	v_fmac_f32_e32 v148, v141, v141
	v_fmac_f32_e32 v148, v142, v142
	v_fmac_f32_e32 v148, v143, v143
	v_fmac_f32_e32 v148, v144, v144
	v_fmac_f32_e32 v148, v145, v145
	v_fmac_f32_e32 v148, v146, v146
	v_fmac_f32_e32 v148, v147, v147
	v_cvt_pk_bf16_f32 v150, v42, v43
	v_cvt_pk_bf16_f32 v151, v44, v45
	global_store_dwordx2 v[158:159], v[150:151], off offset:3072
	ds_bpermute_b32 v150, v80, v148
	s_waitcnt lgkmcnt(0)
; __device__ __forceinline__ unsigned cvt_pk_bf16(float lo, float hi) { unsigned r; asm volatile("v_cvt_pk_bf16_f32 %0, %1, %2" : "=v"(r) : "v"(lo), "v"(hi)); return r; }
; __device__ __forceinline__ float bf_lo(unsigned w) { return __uint_as_float(w << 16); }
; __device__ __forceinline__ float bf_hi(unsigned w) { return __uint_as_float(w & 0xffff0000u); }
; __global__ void __launch_bounds__(512, 2) trunk_fwd(Args args) {
;     ...
;                     float cv[8], uu[8]; float ss = 0.f;
; #pragma unroll
;                     for (int i = 0; i < 4; ++i) {
;                         uu[2 * i] = bf_lo(gu[i]); uu[2 * i + 1] = bf_hi(gu[i]);
;                         cv[2 * i] = bf_lo(gb[i]) * (w0[2 * i] * uu[2 * i] + w1[2 * i] * u1[2 * i] + w2[2 * i] * u2[2 * i]);
;                         cv[2 * i + 1] = bf_hi(gb[i]) * (w0[2 * i + 1] * uu[2 * i + 1] + w1[2 * i + 1] * u1[2 * i + 1] + w2[2 * i + 1] * u2[2 * i + 1]);
;                     }
; #pragma unroll
;                     for (int i = 0; i < 8; ++i) { ss += cv[i] * cv[i]; u2[i] = u1[i]; u1[i] = uu[i]; }
;                     ss = wave_sum(ss);
;                     const float rc = rsqrtf(ss * (1.0f / 512.0f) + EPS);
;                     u32x4 oc;
; #pragma unroll
;                     for (int i = 0; i < 4; ++i) oc[i] = cvt_pk_bf16(cv[2 * i] * rc, cv[2 * i + 1] * rc);
;                     *(u32x4*)(MIX + (size_t)r * 1024 + 512 + c0) = oc;
;                     u32x2 pw; pw.x = cvt_pk_bf16(pv4[0], pv4[1]); pw.y = cvt_pk_bf16(pv4[2], pv4[3]);
;                     *(u32x2*)(PB + (size_t)r * PLE + lane * 4) = pw;
;                 }
	v_add_f32_e32 v148, v148, v150
	ds_bpermute_b32 v150, v81, v148
	s_waitcnt lgkmcnt(0)
	v_add_f32_e32 v148, v148, v150
	ds_bpermute_b32 v150, v82, v148
	s_waitcnt lgkmcnt(0)
	v_add_f32_e32 v148, v148, v150
	ds_bpermute_b32 v150, v83, v148
	s_waitcnt lgkmcnt(0)
	v_add_f32_e32 v148, v148, v150
	ds_bpermute_b32 v150, v84, v148
	s_waitcnt lgkmcnt(0)
	v_add_f32_e32 v148, v148, v150
	ds_bpermute_b32 v150, v85, v148
	s_waitcnt lgkmcnt(0)
	v_add_f32_e32 v148, v148, v150
	v_fmamk_f32 v148, v148, 0x3b000000, v162
	v_mul_f32_e32 v150, 0x4b800000, v148
	v_cmp_gt_f32_e32 vcc, s31, v148
	s_nop 1
	v_cndmask_b32_e32 v148, v148, v150, vcc
	v_rsq_f32_e32 v148, v148
	s_nop 0
	v_mul_f32_e32 v150, 0x45800000, v148
	v_cndmask_b32_e32 v149, v148, v150, vcc
	v_mul_f32_e32 v140, v149, v140
	v_mul_f32_e32 v141, v149, v141
	v_mul_f32_e32 v142, v149, v142
	v_mul_f32_e32 v143, v149, v143
	v_mul_f32_e32 v144, v149, v144
	v_mul_f32_e32 v145, v149, v145
	v_mul_f32_e32 v146, v149, v146
	v_mul_f32_e32 v147, v149, v147
	v_cvt_pk_bf16_f32 v140, v140, v141
	v_cvt_pk_bf16_f32 v141, v142, v143
	v_cvt_pk_bf16_f32 v142, v144, v145
	v_cvt_pk_bf16_f32 v143, v146, v147
	global_store_dwordx4 v[156:157], v[140:143], off
	s_waitcnt vmcnt(7)
	v_lshlrev_b32_e32 v188, 16, v30
	v_and_b32_e32 v189, 0xffff0000, v30
	v_lshlrev_b32_e32 v190, 16, v31
	v_and_b32_e32 v191, 0xffff0000, v31
	v_lshlrev_b32_e32 v192, 16, v32
	v_and_b32_e32 v193, 0xffff0000, v32
	v_lshlrev_b32_e32 v194, 16, v33
	v_and_b32_e32 v195, 0xffff0000, v33
	v_mul_f32_e32 v140, v164, v188
	v_mul_f32_e32 v141, v165, v189
	v_mul_f32_e32 v142, v166, v190
	v_mul_f32_e32 v143, v167, v191
	v_mul_f32_e32 v144, v168, v192
	v_mul_f32_e32 v145, v169, v193
	v_mul_f32_e32 v146, v170, v194
	v_mul_f32_e32 v147, v171, v195
	v_fmac_f32_e32 v140, v172, v204
	v_fmac_f32_e32 v141, v173, v205
	v_fmac_f32_e32 v142, v174, v206
	v_fmac_f32_e32 v143, v175, v207
	v_fmac_f32_e32 v144, v176, v208
	v_fmac_f32_e32 v145, v177, v209
	v_fmac_f32_e32 v146, v178, v210
	v_fmac_f32_e32 v147, v179, v211
	v_fmac_f32_e32 v140, v180, v196
	v_fmac_f32_e32 v141, v181, v197
	v_fmac_f32_e32 v142, v182, v198
	v_fmac_f32_e32 v143, v183, v199
	v_fmac_f32_e32 v144, v184, v200
	v_fmac_f32_e32 v145, v185, v201
	v_fmac_f32_e32 v146, v186, v202
	v_fmac_f32_e32 v147, v187, v203
	v_lshlrev_b32_e32 v150, 16, v14
	v_and_b32_e32 v151, 0xffff0000, v14
	v_mul_f32_e32 v140, v150, v140
	v_mul_f32_e32 v141, v151, v141
	v_lshlrev_b32_e32 v150, 16, v15
	v_and_b32_e32 v151, 0xffff0000, v15
	v_mul_f32_e32 v142, v150, v142
	v_mul_f32_e32 v143, v151, v143
	v_lshlrev_b32_e32 v150, 16, v16
	v_and_b32_e32 v151, 0xffff0000, v16
	v_mul_f32_e32 v144, v150, v144
	v_mul_f32_e32 v145, v151, v145
	v_lshlrev_b32_e32 v150, 16, v17
	v_and_b32_e32 v151, 0xffff0000, v17
	v_mul_f32_e32 v146, v150, v146
	v_mul_f32_e32 v147, v151, v147
	v_mul_f32_e32 v148, v140, v140
	v_fmac_f32_e32 v148, v141, v141
	v_fmac_f32_e32 v148, v142, v142
	v_fmac_f32_e32 v148, v143, v143
	v_fmac_f32_e32 v148, v144, v144
	v_fmac_f32_e32 v148, v145, v145
	v_fmac_f32_e32 v148, v146, v146
	v_fmac_f32_e32 v148, v147, v147
	v_cvt_pk_bf16_f32 v150, v46, v47
	v_cvt_pk_bf16_f32 v151, v48, v49
	global_store_dwordx2 v[158:159], v[150:151], off offset:3584
	v_lshl_add_u64 v[158:159], v[158:159], 0, s[20:21]
	ds_bpermute_b32 v150, v80, v148
	s_waitcnt lgkmcnt(0)
	v_add_f32_e32 v148, v148, v150
	ds_bpermute_b32 v150, v81, v148
	s_waitcnt lgkmcnt(0)
	v_add_f32_e32 v148, v148, v150
	ds_bpermute_b32 v150, v82, v148
	s_waitcnt lgkmcnt(0)
	v_add_f32_e32 v148, v148, v150
	ds_bpermute_b32 v150, v83, v148
	s_waitcnt lgkmcnt(0)
	v_add_f32_e32 v148, v148, v150
	ds_bpermute_b32 v150, v84, v148
	s_waitcnt lgkmcnt(0)
	v_add_f32_e32 v148, v148, v150
	ds_bpermute_b32 v150, v85, v148
	s_waitcnt lgkmcnt(0)
	v_add_f32_e32 v148, v148, v150
	v_fmamk_f32 v148, v148, 0x3b000000, v162
	v_mul_f32_e32 v150, 0x4b800000, v148
	v_cmp_gt_f32_e32 vcc, s31, v148
	s_nop 1
	v_cndmask_b32_e32 v148, v148, v150, vcc
	v_rsq_f32_e32 v148, v148
	s_nop 0
	v_mul_f32_e32 v150, 0x45800000, v148
	v_cndmask_b32_e32 v149, v148, v150, vcc
	v_mul_f32_e32 v140, v149, v140
	v_mul_f32_e32 v141, v149, v141
	v_mul_f32_e32 v142, v149, v142
	v_mul_f32_e32 v143, v149, v143
	v_mul_f32_e32 v144, v149, v144
	v_mul_f32_e32 v145, v149, v145
	v_mul_f32_e32 v146, v149, v146
	v_mul_f32_e32 v147, v149, v147
	v_cvt_pk_bf16_f32 v140, v140, v141
	v_cvt_pk_bf16_f32 v141, v142, v143
	v_cvt_pk_bf16_f32 v142, v144, v145
	v_cvt_pk_bf16_f32 v143, v146, v147
	global_store_dwordx4 v[156:157], v[140:143], off offset:2048
	v_lshl_add_u64 v[156:157], v[156:157], 0, s[20:21]
	s_branch .LBB0_1053
